# uq epilogue: hoist all 16 rowsum loads ahead of the first group, remove per-group load/store-drain waits
# speedup vs baseline: 1.0123x; 1.0006x over previous
; #define GLDS16(gp, lp) __builtin_amdgcn_global_load_lds((const unsigned*)(gp), (__attribute__((address_space(3))) unsigned*)(lp), 16, 0, 0)
; template <bool SWAP, class Epi, bool THIN = false> ...
;     ...
;     if (w < full * 8 * NT) { const int sr = w / (8 * NT), rem = w - sr * 8 * NT; nt = rem >> 3; mt = sr * 8 + (rem & 7); }
;     else { const int w2 = w - full * 8 * NT, rl = MT - full * 8; nt = w2 / rl; mt = full * 8 + (w2 - nt * rl); }
;     unsigned ap[4], bp[4];
; #pragma unroll
;     for (int i = 0; i < 4; ++i) {
;       const int r = (tid >> 3) + 64 * i;
;       const int cs = tid & 7;
;       const int c = ((cs ^ ((r >> 1) & 7)) << 3);
;       const int sub = 2 * mt + (r >> 7);
;       const int g = sub / tpg, ti = sub - g * tpg;
;       int rig = ti * step - halo + (r & 127); rig = rig < 0 ? 0 : (rig > grows - 1 ? grows - 1 : rig);
;       ap[i] = (unsigned)((g * a_gstride + a_goff + rig) * lda + c);
;       int br = nt * 256 + r; br = br > N - 1 ? N - 1 : br;
;       bp[i] = (unsigned)(br * K + c);
;     }
;     const bool have_next = false;
;     f32x4 acc[4][8];
; #pragma unroll
;     for (int m = 0; m < 4; ++m)
; #pragma unroll
;       for (int n = 0; n < 8; ++n) acc[m][n] = (f32x4){0.f, 0.f, 0.f, 0.f};
;     if (!pre_issued) {
; #pragma unroll
;       for (int i = 0; i < 4; ++i) { GLDS16(A + (size_t)ap[i], smem + tid * 16 + i * 8192); GLDS16(Bt + (size_t)bp[i], smem + 32768 + tid * 16 + i * 8192); }
;     }
;     pre_issued = have_next;
;     for (int st = 0; st < ns; ++st) {
;       asm volatile("s_waitcnt vmcnt(0)" ::: "memory");
;       __builtin_amdgcn_s_barrier();
;       asm volatile("" ::: "memory");
;       if (st + 1 < ns) {
;         char* nb = smem + ((st + 1) & 1) * 65536;
;         const int ko = (st + 1) * 64;
; #pragma unroll
;         for (int i = 0; i < 4; ++i) { GLDS16(A + (size_t)(ap[i] + ko), nb + tid * 16 + i * 8192); GLDS16(Bt + (size_t)(bp[i] + ko), nb + 32768 + tid * 16 + i * 8192); }
.LBB0_1749:
	s_mul_hi_i32 s4, s33, 0x2aaaaaab
	s_lshr_b32 s5, s4, 31
	s_ashr_i32 s4, s4, 3
	s_add_i32 s4, s4, s5
	s_lshl_b32 s5, s4, 4
	s_and_b32 s6, s46, 14
	s_or_b32 s5, s5, s6
	v_add_u32_e32 v2, s5, v143
	v_ashrrev_i32_e32 v3, 31, v2
	v_lshrrev_b32_e32 v3, 28, v3
	v_add_u32_e32 v3, v2, v3
	v_ashrrev_i32_e32 v3, 4, v3
	v_lshlrev_b32_e32 v4, 11, v3
	v_lshlrev_b32_e32 v2, 7, v2
	v_sub_u32_e32 v2, v2, v4
	v_or_b32_e32 v4, v2, v144
	v_min_i32_e32 v4, 0x7ff, v4
	s_mulk_i32 s4, 0xfa00
	v_lshlrev_b32_e32 v4, 9, v4
	v_cmp_lt_i32_e32 vcc, -1, v2
	s_add_i32 s4, s48, s4
	s_and_b32 s4, s4, 0xffffff00
	v_cndmask_b32_e32 v2, 0, v4, vcc
	v_lshl_add_u32 v2, v3, 20, v2
	v_or_b32_e32 v130, v2, v141
	v_add_u32_e32 v2, s4, v140
	v_min_i32_e32 v2, 0x5ff, v2
	v_lshl_or_b32 v4, v2, 9, v141
	v_add_u32_e32 v2, s5, v146
	v_ashrrev_i32_e32 v3, 31, v2
	v_lshrrev_b32_e32 v3, 28, v3
	v_add_u32_e32 v3, v2, v3
	v_ashrrev_i32_e32 v3, 4, v3
	v_lshlrev_b32_e32 v5, 11, v3
	v_lshlrev_b32_e32 v2, 7, v2
	v_sub_u32_e32 v2, v2, v5
	v_or_b32_e32 v5, v2, v147
	v_min_i32_e32 v5, 0x7ff, v5
	v_lshlrev_b32_e32 v5, 9, v5
	v_cmp_lt_i32_e32 vcc, -1, v2
	v_readfirstlane_b32 s44, v142
	s_mov_b32 m0, s44
	v_cndmask_b32_e32 v2, 0, v5, vcc
	v_lshl_add_u32 v2, v3, 20, v2
	v_or_b32_e32 v6, v2, v141
	v_add_u32_e32 v2, s4, v145
	v_min_i32_e32 v2, 0x5ff, v2
	v_lshl_or_b32 v8, v2, 9, v141
	v_add_u32_e32 v2, s5, v149
	v_ashrrev_i32_e32 v3, 31, v2
	v_lshrrev_b32_e32 v3, 28, v3
	v_add_u32_e32 v3, v2, v3
	v_ashrrev_i32_e32 v3, 4, v3
	v_lshlrev_b32_e32 v5, 11, v3
	v_lshlrev_b32_e32 v2, 7, v2
	v_sub_u32_e32 v2, v2, v5
	v_or_b32_e32 v5, v2, v144
	v_min_i32_e32 v5, 0x7ff, v5
	v_lshlrev_b32_e32 v5, 9, v5
	v_cmp_lt_i32_e32 vcc, -1, v2
	v_readfirstlane_b32 s14, v153
	v_mov_b32_e32 v7, v131
	v_cndmask_b32_e32 v2, 0, v5, vcc
	v_lshl_add_u32 v2, v3, 20, v2
	v_or_b32_e32 v10, v2, v141
	v_add_u32_e32 v2, s4, v148
	v_min_i32_e32 v2, 0x5ff, v2
	v_lshl_or_b32 v12, v2, 9, v141
	v_add_u32_e32 v2, s5, v151
	v_ashrrev_i32_e32 v3, 31, v2
	v_lshrrev_b32_e32 v3, 28, v3
	v_add_u32_e32 v3, v2, v3
	v_ashrrev_i32_e32 v3, 4, v3
	v_lshlrev_b32_e32 v5, 11, v3
	v_lshlrev_b32_e32 v2, 7, v2
	v_sub_u32_e32 v2, v2, v5
	v_or_b32_e32 v5, v2, v152
	v_min_i32_e32 v5, 0x7ff, v5
	v_lshlrev_b32_e32 v5, 9, v5
	v_cmp_lt_i32_e32 vcc, -1, v2
	v_readfirstlane_b32 s15, v154
	v_lshl_add_u64 v[6:7], v[6:7], 1, s[24:25]
	v_cndmask_b32_e32 v2, 0, v5, vcc
	v_lshl_add_u32 v2, v3, 20, v2
	v_or_b32_e32 v14, v2, v141
	v_add_u32_e32 v2, s4, v150
	v_min_i32_e32 v2, 0x5ff, v2
	v_lshl_or_b32 v16, v2, 9, v141
	v_lshl_add_u64 v[2:3], v[130:131], 1, s[24:25]
	v_mov_b32_e32 v5, v131
	global_load_lds_dwordx4 v[2:3], off
	v_lshl_add_u64 v[4:5], v[4:5], 1, s[26:27]
	s_mov_b32 m0, s14
	v_mov_b32_e32 v9, v131
	global_load_lds_dwordx4 v[4:5], off
	s_mov_b32 m0, s15
	v_readfirstlane_b32 s16, v155
	global_load_lds_dwordx4 v[6:7], off
	v_lshl_add_u64 v[8:9], v[8:9], 1, s[26:27]
	s_mov_b32 m0, s16
	v_mov_b32_e32 v11, v131
	v_readfirstlane_b32 s17, v156
	global_load_lds_dwordx4 v[8:9], off
	v_lshl_add_u64 v[10:11], v[10:11], 1, s[24:25]
	s_mov_b32 m0, s17
	v_mov_b32_e32 v13, v131
	v_readfirstlane_b32 s18, v157
	global_load_lds_dwordx4 v[10:11], off
	v_lshl_add_u64 v[12:13], v[12:13], 1, s[26:27]
	s_mov_b32 m0, s18
	v_mov_b32_e32 v15, v131
	v_readfirstlane_b32 s19, v158
	global_load_lds_dwordx4 v[12:13], off
	v_lshl_add_u64 v[14:15], v[14:15], 1, s[24:25]
	s_mov_b32 m0, s19
	v_mov_b32_e32 v17, v131
	v_readfirstlane_b32 s45, v159
	global_load_lds_dwordx4 v[14:15], off
	v_lshl_add_u64 v[16:17], v[16:17], 1, s[26:27]
	s_mov_b32 m0, s45
	v_readfirstlane_b32 s13, v160
	global_load_lds_dwordx4 v[16:17], off
	s_waitcnt vmcnt(0)
	s_barrier
	v_lshl_add_u64 v[18:19], v[2:3], 0, s[28:29]
	s_mov_b32 m0, s13
	v_readfirstlane_b32 s8, v161
	global_load_lds_dwordx4 v[18:19], off
	v_lshl_add_u64 v[18:19], v[4:5], 0, s[28:29]
	s_mov_b32 m0, s8
	v_readfirstlane_b32 s7, v162
	global_load_lds_dwordx4 v[18:19], off
	v_lshl_add_u64 v[18:19], v[6:7], 0, s[28:29]
	s_mov_b32 m0, s7
	v_readfirstlane_b32 s6, v163
	global_load_lds_dwordx4 v[18:19], off
	v_lshl_add_u64 v[18:19], v[8:9], 0, s[28:29]
	s_mov_b32 m0, s6
	v_readfirstlane_b32 s9, v164
	global_load_lds_dwordx4 v[18:19], off
	v_lshl_add_u64 v[18:19], v[10:11], 0, s[28:29]
	s_mov_b32 m0, s9
	v_readfirstlane_b32 s10, v165
	global_load_lds_dwordx4 v[18:19], off
	v_lshl_add_u64 v[18:19], v[12:13], 0, s[28:29]
	s_mov_b32 m0, s10
	v_readfirstlane_b32 s11, v166
	global_load_lds_dwordx4 v[18:19], off
	v_lshl_add_u64 v[18:19], v[14:15], 0, s[28:29]
	s_mov_b32 m0, s11
	v_readfirstlane_b32 s12, v167
	global_load_lds_dwordx4 v[18:19], off
	v_lshl_add_u64 v[18:19], v[16:17], 0, s[28:29]
	s_mov_b32 m0, s12
	s_nop 0
	global_load_lds_dwordx4 v[18:19], off
	ds_read_b128 v[18:21], v168
	ds_read_b128 v[22:25], v168 offset:2048
	ds_read_b128 v[26:29], v168 offset:4096
	ds_read_b128 v[30:33], v168 offset:6144
	ds_read_b128 v[34:37], v169 offset:32768
	ds_read_b128 v[38:41], v169 offset:34816
	ds_read_b128 v[42:45], v169 offset:36864
	ds_read_b128 v[46:49], v169 offset:38912
	ds_read_b128 v[74:77], v169 offset:40960
	ds_read_b128 v[78:81], v169 offset:43008
	s_waitcnt lgkmcnt(0)
; template <bool SWAP, class Epi, bool THIN = false> ...
;     ...
;       bf16x8 afA[4], afB[4], bfb[2][2];
; #pragma unroll
;       for (int m = 0; m < 4; ++m) afA[m] = *(const bf16x8*)(sa + m * 2048 + ((fq ^ swz) << 4));
; #pragma unroll
;       for (int n = 0; n < 2; ++n) bfb[0][n] = *(const bf16x8*)(sb + n * 2048 + ((fq ^ swz) << 4));
; #pragma unroll
;       for (int gq = 0; gq < 8; ++gq) {
;         const int ks = gq >> 2, nh = gq & 3;
;         if (gq < 7) {
;           const int ks2 = (gq + 1) >> 2, nh2 = (gq + 1) & 3;
; #pragma unroll
;           for (int n = 0; n < 2; ++n) bfb[(gq + 1) & 1][n] = *(const bf16x8*)(sb + (nh2 * 2 + n) * 2048 + (((ks2 * 4 + fq) ^ swz) << 4));
;         }
;         if (gq == 3) {
; #pragma unroll
;           for (int m = 0; m < 4; ++m) afB[m] = *(const bf16x8*)(sa + m * 2048 + (((4 + fq) ^ swz) << 4));
;         }
;         __builtin_amdgcn_sched_barrier(0);
; #pragma unroll
;         for (int m = 0; m < 4; ++m)
; #pragma unroll
;           for (int n = 0; n < 2; ++n) {
;             const bf16x8 av = ks ? afB[m] : afA[m];
;             acc[m][nh * 2 + n] = SWAP ? __builtin_amdgcn_mfma_f32_16x16x32_bf16(bfb[gq & 1][n], av, acc[m][nh * 2 + n], 0, 0, 0)
;                                       : __builtin_amdgcn_mfma_f32_16x16x32_bf16(av, bfb[gq & 1][n], acc[m][nh * 2 + n], 0, 0, 0);
;           }
	v_mfma_f32_16x16x32_bf16 v[50:53], v[34:37], v[18:21], 0
	v_mfma_f32_16x16x32_bf16 v[54:57], v[38:41], v[18:21], 0
	v_mfma_f32_16x16x32_bf16 v[58:61], v[34:37], v[22:25], 0
	v_mfma_f32_16x16x32_bf16 v[62:65], v[38:41], v[22:25], 0
	v_mfma_f32_16x16x32_bf16 v[66:69], v[34:37], v[26:29], 0
	v_mfma_f32_16x16x32_bf16 v[70:73], v[38:41], v[26:29], 0
	v_mfma_f32_16x16x32_bf16 v[34:37], v[34:37], v[30:33], 0
	v_mfma_f32_16x16x32_bf16 v[38:41], v[38:41], v[30:33], 0
	ds_read_b128 v[106:109], v169 offset:45056
	ds_read_b128 v[110:113], v169 offset:47104
	v_mfma_f32_16x16x32_bf16 v[82:85], v[42:45], v[18:21], 0
	v_mfma_f32_16x16x32_bf16 v[86:89], v[46:49], v[18:21], 0
	v_mfma_f32_16x16x32_bf16 v[90:93], v[42:45], v[22:25], 0
	v_mfma_f32_16x16x32_bf16 v[94:97], v[46:49], v[22:25], 0
	v_mfma_f32_16x16x32_bf16 v[98:101], v[42:45], v[26:29], 0
	v_mfma_f32_16x16x32_bf16 v[102:105], v[46:49], v[26:29], 0
	v_mfma_f32_16x16x32_bf16 v[42:45], v[42:45], v[30:33], 0
	v_mfma_f32_16x16x32_bf16 v[46:49], v[46:49], v[30:33], 0
	ds_read_b128 v[178:181], v170 offset:32768
	ds_read_b128 v[182:185], v170 offset:34816
	ds_read_b128 v[186:189], v171
	ds_read_b128 v[190:193], v171 offset:2048
	ds_read_b128 v[194:197], v171 offset:4096
	ds_read_b128 v[198:201], v171 offset:6144
	v_mfma_f32_16x16x32_bf16 v[114:117], v[74:77], v[18:21], 0
	v_mfma_f32_16x16x32_bf16 v[118:121], v[78:81], v[18:21], 0
	v_mfma_f32_16x16x32_bf16 v[122:125], v[74:77], v[22:25], 0
	v_mfma_f32_16x16x32_bf16 v[126:129], v[78:81], v[22:25], 0
	v_mfma_f32_16x16x32_bf16 v[132:135], v[74:77], v[26:29], 0
	v_mfma_f32_16x16x32_bf16 v[136:139], v[78:81], v[26:29], 0
	v_mfma_f32_16x16x32_bf16 v[74:77], v[74:77], v[30:33], 0
	v_mfma_f32_16x16x32_bf16 v[78:81], v[78:81], v[30:33], 0
	ds_read_b128 v[214:217], v170 offset:36864
	ds_read_b128 v[218:221], v170 offset:38912
	s_waitcnt lgkmcnt(0)
	v_mfma_f32_16x16x32_bf16 v[202:205], v[106:109], v[18:21], 0
	v_mfma_f32_16x16x32_bf16 v[18:21], v[110:113], v[18:21], 0
	v_mfma_f32_16x16x32_bf16 v[206:209], v[106:109], v[22:25], 0
	v_mfma_f32_16x16x32_bf16 v[22:25], v[110:113], v[22:25], 0
	v_mfma_f32_16x16x32_bf16 v[210:213], v[106:109], v[26:29], 0
	v_mfma_f32_16x16x32_bf16 v[26:29], v[110:113], v[26:29], 0
	v_mfma_f32_16x16x32_bf16 v[106:109], v[106:109], v[30:33], 0
	v_mfma_f32_16x16x32_bf16 v[30:33], v[110:113], v[30:33], 0
	v_mfma_f32_16x16x32_bf16 v[50:53], v[178:181], v[186:189], v[50:53]
	v_mfma_f32_16x16x32_bf16 v[58:61], v[178:181], v[190:193], v[58:61]
	v_mfma_f32_16x16x32_bf16 v[66:69], v[178:181], v[194:197], v[66:69]
	v_mfma_f32_16x16x32_bf16 v[34:37], v[178:181], v[198:201], v[34:37]
	ds_read_b128 v[110:113], v170 offset:40960
	ds_read_b128 v[178:181], v170 offset:43008
	v_mfma_f32_16x16x32_bf16 v[54:57], v[182:185], v[186:189], v[54:57]
	v_mfma_f32_16x16x32_bf16 v[62:65], v[182:185], v[190:193], v[62:65]
	v_mfma_f32_16x16x32_bf16 v[70:73], v[182:185], v[194:197], v[70:73]
	v_mfma_f32_16x16x32_bf16 v[38:41], v[182:185], v[198:201], v[38:41]
	v_mfma_f32_16x16x32_bf16 v[82:85], v[214:217], v[186:189], v[82:85]
	v_mfma_f32_16x16x32_bf16 v[90:93], v[214:217], v[190:193], v[90:93]
	v_mfma_f32_16x16x32_bf16 v[98:101], v[214:217], v[194:197], v[98:101]
	v_mfma_f32_16x16x32_bf16 v[42:45], v[214:217], v[198:201], v[42:45]
	ds_read_b128 v[182:185], v170 offset:45056
	ds_read_b128 v[214:217], v170 offset:47104
	v_mfma_f32_16x16x32_bf16 v[86:89], v[218:221], v[186:189], v[86:89]
	v_mfma_f32_16x16x32_bf16 v[94:97], v[218:221], v[190:193], v[94:97]
	v_mfma_f32_16x16x32_bf16 v[102:105], v[218:221], v[194:197], v[102:105]
	v_mfma_f32_16x16x32_bf16 v[46:49], v[218:221], v[198:201], v[46:49]
	s_waitcnt lgkmcnt(0)
	v_mfma_f32_16x16x32_bf16 v[114:117], v[110:113], v[186:189], v[114:117]
	v_mfma_f32_16x16x32_bf16 v[118:121], v[178:181], v[186:189], v[118:121]
	v_mfma_f32_16x16x32_bf16 v[122:125], v[110:113], v[190:193], v[122:125]
	v_mfma_f32_16x16x32_bf16 v[126:129], v[178:181], v[190:193], v[126:129]
	v_mfma_f32_16x16x32_bf16 v[132:135], v[110:113], v[194:197], v[132:135]
	v_mfma_f32_16x16x32_bf16 v[136:139], v[178:181], v[194:197], v[136:139]
	v_mfma_f32_16x16x32_bf16 v[74:77], v[110:113], v[198:201], v[74:77]
	v_mfma_f32_16x16x32_bf16 v[78:81], v[178:181], v[198:201], v[78:81]
	s_mov_b32 m0, s44
	v_mfma_f32_16x16x32_bf16 v[110:113], v[182:185], v[186:189], v[202:205]
	s_waitcnt vmcnt(0)
	s_barrier
; template <bool SWAP, class Epi, bool THIN = false> ...
;     ...
;     for (int st = 0; st < ns; ++st) {
;       asm volatile("s_waitcnt vmcnt(0)" ::: "memory");
;       __builtin_amdgcn_s_barrier();
;       asm volatile("" ::: "memory");
;       if (st + 1 < ns) {
;         char* nb = smem + ((st + 1) & 1) * 65536;
;         const int ko = (st + 1) * 64;
; #pragma unroll
;         for (int i = 0; i < 4; ++i) { GLDS16(A + (size_t)(ap[i] + ko), nb + tid * 16 + i * 8192); GLDS16(Bt + (size_t)(bp[i] + ko), nb + 32768 + tid * 16 + i * 8192); }
;       }
;       const char* sa = smem + (st & 1) * 65536 + (wr * 64 + fr) * 128;
;       const char* sb = smem + (st & 1) * 65536 + 32768 + (wc * 128 + fr) * 128;
;       if constexpr (THIN) {
;         if (wc == 0) {
; #pragma unroll
;           for (int ks = 0; ks < 2; ++ks) {
;             bf16x8 af[4], bf[2];
; #pragma unroll
;             for (int m = 0; m < 4; ++m) af[m] = *(const bf16x8*)(sa + m * 2048 + (((ks * 4 + fq) ^ swz) << 4));
; #pragma unroll
;             for (int n = 0; n < 2; ++n) bf[n] = *(const bf16x8*)(sb + n * 2048 + (((ks * 4 + fq) ^ swz) << 4));
; #pragma unroll
;             for (int m = 0; m < 4; ++m)
; #pragma unroll
;               for (int n = 0; n < 2; ++n)
;                 acc[m][n] = SWAP ? __builtin_amdgcn_mfma_f32_16x16x32_bf16(bf[n], af[m], acc[m][n], 0, 0, 0)
;                                  : __builtin_amdgcn_mfma_f32_16x16x32_bf16(af[m], bf[n], acc[m][n], 0, 0, 0);
;           }
;         }
;       } else {
;       bf16x8 afA[4], afB[4], bfb[2][2];
; #pragma unroll
;       for (int m = 0; m < 4; ++m) afA[m] = *(const bf16x8*)(sa + m * 2048 + ((fq ^ swz) << 4));
; #pragma unroll
;       for (int n = 0; n < 2; ++n) bfb[0][n] = *(const bf16x8*)(sb + n * 2048 + ((fq ^ swz) << 4));
; #pragma unroll
;       for (int gq = 0; gq < 8; ++gq) {
;         const int ks = gq >> 2, nh = gq & 3;
;         if (gq < 7) {
;           const int ks2 = (gq + 1) >> 2, nh2 = (gq + 1) & 3;
; #pragma unroll
;           for (int n = 0; n < 2; ++n) bfb[(gq + 1) & 1][n] = *(const bf16x8*)(sb + (nh2 * 2 + n) * 2048 + (((ks2 * 4 + fq) ^ swz) << 4));
;         }
;         if (gq == 3) {
; #pragma unroll
;           for (int m = 0; m < 4; ++m) afB[m] = *(const bf16x8*)(sa + m * 2048 + (((4 + fq) ^ swz) << 4));
;         }
;         __builtin_amdgcn_sched_barrier(0);
; #pragma unroll
	v_mfma_f32_16x16x32_bf16 v[18:21], v[214:217], v[186:189], v[18:21]
	v_lshl_add_u64 v[186:187], v[2:3], 0, s[30:31]
	global_load_lds_dwordx4 v[186:187], off
	v_lshl_add_u64 v[186:187], v[4:5], 0, s[30:31]
	s_mov_b32 m0, s14
	v_mfma_f32_16x16x32_bf16 v[178:181], v[182:185], v[190:193], v[206:209]
	global_load_lds_dwordx4 v[186:187], off
	s_mov_b32 m0, s15
	v_mfma_f32_16x16x32_bf16 v[22:25], v[214:217], v[190:193], v[22:25]
	v_lshl_add_u64 v[190:191], v[6:7], 0, s[30:31]
	global_load_lds_dwordx4 v[190:191], off
	v_lshl_add_u64 v[190:191], v[8:9], 0, s[30:31]
	s_mov_b32 m0, s16
	v_mfma_f32_16x16x32_bf16 v[186:189], v[182:185], v[194:197], v[210:213]
	global_load_lds_dwordx4 v[190:191], off
	v_lshl_add_u64 v[190:191], v[10:11], 0, s[30:31]
	s_mov_b32 m0, s17
	v_mfma_f32_16x16x32_bf16 v[26:29], v[214:217], v[194:197], v[26:29]
	global_load_lds_dwordx4 v[190:191], off
	v_lshl_add_u64 v[190:191], v[12:13], 0, s[30:31]
	s_mov_b32 m0, s18
	v_mfma_f32_16x16x32_bf16 v[106:109], v[182:185], v[198:201], v[106:109]
	global_load_lds_dwordx4 v[190:191], off
	v_lshl_add_u64 v[190:191], v[14:15], 0, s[30:31]
	s_mov_b32 m0, s19
	v_mfma_f32_16x16x32_bf16 v[30:33], v[214:217], v[198:201], v[30:33]
	global_load_lds_dwordx4 v[190:191], off
	v_lshl_add_u64 v[190:191], v[16:17], 0, s[30:31]
	s_mov_b32 m0, s45
	s_nop 0
	global_load_lds_dwordx4 v[190:191], off
	ds_read_b128 v[182:185], v172
	ds_read_b128 v[190:193], v172 offset:2048
	ds_read_b128 v[194:197], v172 offset:4096
	ds_read_b128 v[202:205], v172 offset:6144
	ds_read_b128 v[206:209], v173
	ds_read_b128 v[210:213], v173 offset:2048
	ds_read_b128 v[218:221], v173 offset:4096
	ds_read_b128 v[222:225], v173 offset:6144
	s_waitcnt lgkmcnt(0)
	v_mfma_f32_16x16x32_bf16 v[50:53], v[206:209], v[182:185], v[50:53]
	v_mfma_f32_16x16x32_bf16 v[58:61], v[206:209], v[190:193], v[58:61]
	v_mfma_f32_16x16x32_bf16 v[66:69], v[206:209], v[194:197], v[66:69]
	v_mfma_f32_16x16x32_bf16 v[34:37], v[206:209], v[202:205], v[34:37]
	ds_read_b128 v[198:201], v173 offset:8192
	ds_read_b128 v[206:209], v173 offset:10240
	v_mfma_f32_16x16x32_bf16 v[54:57], v[210:213], v[182:185], v[54:57]
	v_mfma_f32_16x16x32_bf16 v[62:65], v[210:213], v[190:193], v[62:65]
	v_mfma_f32_16x16x32_bf16 v[70:73], v[210:213], v[194:197], v[70:73]
	v_mfma_f32_16x16x32_bf16 v[38:41], v[210:213], v[202:205], v[38:41]
	ds_read_b128 v[210:213], v173 offset:12288
	ds_read_b128 v[214:217], v173 offset:14336
	v_mfma_f32_16x16x32_bf16 v[82:85], v[218:221], v[182:185], v[82:85]
	v_mfma_f32_16x16x32_bf16 v[86:89], v[222:225], v[182:185], v[86:89]
	v_mfma_f32_16x16x32_bf16 v[90:93], v[218:221], v[190:193], v[90:93]
	v_mfma_f32_16x16x32_bf16 v[94:97], v[222:225], v[190:193], v[94:97]
	v_mfma_f32_16x16x32_bf16 v[98:101], v[218:221], v[194:197], v[98:101]
	v_mfma_f32_16x16x32_bf16 v[102:105], v[222:225], v[194:197], v[102:105]
	v_mfma_f32_16x16x32_bf16 v[42:45], v[218:221], v[202:205], v[42:45]
	v_mfma_f32_16x16x32_bf16 v[46:49], v[222:225], v[202:205], v[46:49]
	s_waitcnt lgkmcnt(0)
	v_mfma_f32_16x16x32_bf16 v[114:117], v[198:201], v[182:185], v[114:117]
	ds_read_b128 v[218:221], v174
	ds_read_b128 v[222:225], v174 offset:2048
	v_mfma_f32_16x16x32_bf16 v[122:125], v[198:201], v[190:193], v[122:125]
	v_mfma_f32_16x16x32_bf16 v[132:135], v[198:201], v[194:197], v[132:135]
	v_mfma_f32_16x16x32_bf16 v[74:77], v[198:201], v[202:205], v[74:77]
	ds_read_b128 v[198:201], v175
	ds_read_b128 v[226:229], v175 offset:2048
	ds_read_b128 v[230:233], v175 offset:4096
	ds_read_b128 v[234:237], v175 offset:6144
	v_mfma_f32_16x16x32_bf16 v[118:121], v[206:209], v[182:185], v[118:121]
	v_mfma_f32_16x16x32_bf16 v[126:129], v[206:209], v[190:193], v[126:129]
	v_mfma_f32_16x16x32_bf16 v[136:139], v[206:209], v[194:197], v[136:139]
	v_mfma_f32_16x16x32_bf16 v[78:81], v[206:209], v[202:205], v[78:81]
	v_mfma_f32_16x16x32_bf16 v[110:113], v[210:213], v[182:185], v[110:113]
	v_mfma_f32_16x16x32_bf16 v[18:21], v[214:217], v[182:185], v[18:21]
	v_mfma_f32_16x16x32_bf16 v[178:181], v[210:213], v[190:193], v[178:181]
	v_mfma_f32_16x16x32_bf16 v[22:25], v[214:217], v[190:193], v[22:25]
	v_mfma_f32_16x16x32_bf16 v[182:185], v[210:213], v[194:197], v[186:189]
	s_nop 2
	ds_read_b128 v[186:189], v174 offset:4096
	ds_read_b128 v[190:193], v174 offset:6144
	v_mfma_f32_16x16x32_bf16 v[26:29], v[214:217], v[194:197], v[26:29]
	v_mfma_f32_16x16x32_bf16 v[106:109], v[210:213], v[202:205], v[106:109]
	v_mfma_f32_16x16x32_bf16 v[30:33], v[214:217], v[202:205], v[30:33]
	ds_read_b128 v[194:197], v174 offset:8192
	ds_read_b128 v[202:205], v174 offset:10240
	s_waitcnt lgkmcnt(0)
	v_mfma_f32_16x16x32_bf16 v[50:53], v[218:221], v[198:201], v[50:53]
	v_mfma_f32_16x16x32_bf16 v[54:57], v[222:225], v[198:201], v[54:57]
	v_mfma_f32_16x16x32_bf16 v[58:61], v[218:221], v[226:229], v[58:61]
	v_mfma_f32_16x16x32_bf16 v[62:65], v[222:225], v[226:229], v[62:65]
	v_mfma_f32_16x16x32_bf16 v[66:69], v[218:221], v[230:233], v[66:69]
	v_mfma_f32_16x16x32_bf16 v[70:73], v[222:225], v[230:233], v[70:73]
	v_mfma_f32_16x16x32_bf16 v[34:37], v[218:221], v[234:237], v[34:37]
	v_mfma_f32_16x16x32_bf16 v[38:41], v[222:225], v[234:237], v[38:41]
	v_mfma_f32_16x16x32_bf16 v[82:85], v[186:189], v[198:201], v[82:85]
	v_mfma_f32_16x16x32_bf16 v[90:93], v[186:189], v[226:229], v[90:93]
	v_mfma_f32_16x16x32_bf16 v[98:101], v[186:189], v[230:233], v[98:101]
	v_mfma_f32_16x16x32_bf16 v[42:45], v[186:189], v[234:237], v[42:45]
	ds_read_b128 v[186:189], v174 offset:12288
	ds_read_b128 v[206:209], v174 offset:14336
	v_mfma_f32_16x16x32_bf16 v[86:89], v[190:193], v[198:201], v[86:89]
	v_mfma_f32_16x16x32_bf16 v[94:97], v[190:193], v[226:229], v[94:97]
	v_mfma_f32_16x16x32_bf16 v[102:105], v[190:193], v[230:233], v[102:105]
	v_mfma_f32_16x16x32_bf16 v[46:49], v[190:193], v[234:237], v[46:49]
	v_mfma_f32_16x16x32_bf16 v[114:117], v[194:197], v[198:201], v[114:117]
	v_mfma_f32_16x16x32_bf16 v[118:121], v[202:205], v[198:201], v[118:121]
	v_mfma_f32_16x16x32_bf16 v[122:125], v[194:197], v[226:229], v[122:125]
	v_mfma_f32_16x16x32_bf16 v[126:129], v[202:205], v[226:229], v[126:129]
	v_mfma_f32_16x16x32_bf16 v[132:135], v[194:197], v[230:233], v[132:135]
	v_mfma_f32_16x16x32_bf16 v[136:139], v[202:205], v[230:233], v[136:139]
	v_mfma_f32_16x16x32_bf16 v[74:77], v[194:197], v[234:237], v[74:77]
	v_mfma_f32_16x16x32_bf16 v[78:81], v[202:205], v[234:237], v[78:81]
	s_mov_b32 m0, s13
	s_waitcnt vmcnt(0)
	s_barrier
; template <bool SWAP, class Epi, bool THIN = false> ...
;     ...
;     for (int st = 0; st < ns; ++st) {
;       asm volatile("s_waitcnt vmcnt(0)" ::: "memory");
;       __builtin_amdgcn_s_barrier();
;       asm volatile("" ::: "memory");
;       if (st + 1 < ns) {
;         char* nb = smem + ((st + 1) & 1) * 65536;
;         const int ko = (st + 1) * 64;
; #pragma unroll
;         for (int i = 0; i < 4; ++i) { GLDS16(A + (size_t)(ap[i] + ko), nb + tid * 16 + i * 8192); GLDS16(Bt + (size_t)(bp[i] + ko), nb + 32768 + tid * 16 + i * 8192); }
;       }
;       const char* sa = smem + (st & 1) * 65536 + (wr * 64 + fr) * 128;
;       const char* sb = smem + (st & 1) * 65536 + 32768 + (wc * 128 + fr) * 128;
;       if constexpr (THIN) {
;         if (wc == 0) {
; #pragma unroll
;           for (int ks = 0; ks < 2; ++ks) {
;             bf16x8 af[4], bf[2];
; #pragma unroll
;             for (int m = 0; m < 4; ++m) af[m] = *(const bf16x8*)(sa + m * 2048 + (((ks * 4 + fq) ^ swz) << 4));
; #pragma unroll
;             for (int n = 0; n < 2; ++n) bf[n] = *(const bf16x8*)(sb + n * 2048 + (((ks * 4 + fq) ^ swz) << 4));
; #pragma unroll
;             for (int m = 0; m < 4; ++m)
; #pragma unroll
;               for (int n = 0; n < 2; ++n)
;                 acc[m][n] = SWAP ? __builtin_amdgcn_mfma_f32_16x16x32_bf16(bf[n], af[m], acc[m][n], 0, 0, 0)
;                                  : __builtin_amdgcn_mfma_f32_16x16x32_bf16(af[m], bf[n], acc[m][n], 0, 0, 0);
;           }
;         }
;       } else {
;       bf16x8 afA[4], afB[4], bfb[2][2];
; #pragma unroll
;       for (int m = 0; m < 4; ++m) afA[m] = *(const bf16x8*)(sa + m * 2048 + ((fq ^ swz) << 4));
; #pragma unroll
;       for (int n = 0; n < 2; ++n) bfb[0][n] = *(const bf16x8*)(sb + n * 2048 + ((fq ^ swz) << 4));
; #pragma unroll
;       for (int gq = 0; gq < 8; ++gq) {
;         const int ks = gq >> 2, nh = gq & 3;
;         if (gq < 7) {
;           const int ks2 = (gq + 1) >> 2, nh2 = (gq + 1) & 3;
; #pragma unroll
;           for (int n = 0; n < 2; ++n) bfb[(gq + 1) & 1][n] = *(const bf16x8*)(sb + (nh2 * 2 + n) * 2048 + (((ks2 * 4 + fq) ^ swz) << 4));
;         }
;         if (gq == 3) {
; #pragma unroll
;           for (int m = 0; m < 4; ++m) afB[m] = *(const bf16x8*)(sa + m * 2048 + (((4 + fq) ^ swz) << 4));
;         }
;         __builtin_amdgcn_sched_barrier(0);
; #pragma unroll
	v_lshl_add_u64 v[190:191], v[2:3], 0, s[34:35]
	global_load_lds_dwordx4 v[190:191], off
	v_lshl_add_u64 v[190:191], v[4:5], 0, s[34:35]
	s_mov_b32 m0, s8
	s_waitcnt lgkmcnt(0)
	v_mfma_f32_16x16x32_bf16 v[110:113], v[186:189], v[198:201], v[110:113]
	global_load_lds_dwordx4 v[190:191], off
	v_lshl_add_u64 v[190:191], v[6:7], 0, s[34:35]
	s_mov_b32 m0, s7
	v_mfma_f32_16x16x32_bf16 v[18:21], v[206:209], v[198:201], v[18:21]
	global_load_lds_dwordx4 v[190:191], off
	v_lshl_add_u64 v[190:191], v[8:9], 0, s[34:35]
	s_mov_b32 m0, s6
	v_mfma_f32_16x16x32_bf16 v[178:181], v[186:189], v[226:229], v[178:181]
	global_load_lds_dwordx4 v[190:191], off
	v_lshl_add_u64 v[190:191], v[10:11], 0, s[34:35]
	s_mov_b32 m0, s9
	v_mfma_f32_16x16x32_bf16 v[182:185], v[186:189], v[230:233], v[182:185]
	global_load_lds_dwordx4 v[190:191], off
	v_lshl_add_u64 v[190:191], v[12:13], 0, s[34:35]
	s_mov_b32 m0, s10
	v_mfma_f32_16x16x32_bf16 v[106:109], v[186:189], v[234:237], v[106:109]
	global_load_lds_dwordx4 v[190:191], off
	v_lshl_add_u64 v[190:191], v[14:15], 0, s[34:35]
	s_mov_b32 m0, s11
	v_mfma_f32_16x16x32_bf16 v[22:25], v[206:209], v[226:229], v[22:25]
	global_load_lds_dwordx4 v[190:191], off
	v_lshl_add_u64 v[190:191], v[16:17], 0, s[34:35]
	s_mov_b32 m0, s12
	v_mfma_f32_16x16x32_bf16 v[26:29], v[206:209], v[230:233], v[26:29]
	global_load_lds_dwordx4 v[190:191], off
	ds_read_b128 v[186:189], v168
	ds_read_b128 v[190:193], v168 offset:2048
	ds_read_b128 v[194:197], v168 offset:4096
	ds_read_b128 v[198:201], v168 offset:6144
	ds_read_b128 v[202:205], v169 offset:32768
	ds_read_b128 v[210:213], v169 offset:34816
	ds_read_b128 v[214:217], v169 offset:36864
	ds_read_b128 v[218:221], v169 offset:38912
	v_mfma_f32_16x16x32_bf16 v[30:33], v[206:209], v[234:237], v[30:33]
	s_waitcnt lgkmcnt(0)
	v_mfma_f32_16x16x32_bf16 v[50:53], v[202:205], v[186:189], v[50:53]
	v_mfma_f32_16x16x32_bf16 v[58:61], v[202:205], v[190:193], v[58:61]
	v_mfma_f32_16x16x32_bf16 v[66:69], v[202:205], v[194:197], v[66:69]
	v_mfma_f32_16x16x32_bf16 v[34:37], v[202:205], v[198:201], v[34:37]
	ds_read_b128 v[202:205], v169 offset:40960
	ds_read_b128 v[206:209], v169 offset:43008
	v_mfma_f32_16x16x32_bf16 v[54:57], v[210:213], v[186:189], v[54:57]
	v_mfma_f32_16x16x32_bf16 v[62:65], v[210:213], v[190:193], v[62:65]
	v_mfma_f32_16x16x32_bf16 v[70:73], v[210:213], v[194:197], v[70:73]
	v_mfma_f32_16x16x32_bf16 v[38:41], v[210:213], v[198:201], v[38:41]
	v_mfma_f32_16x16x32_bf16 v[82:85], v[214:217], v[186:189], v[82:85]
	v_mfma_f32_16x16x32_bf16 v[90:93], v[214:217], v[190:193], v[90:93]
	v_mfma_f32_16x16x32_bf16 v[98:101], v[214:217], v[194:197], v[98:101]
	v_mfma_f32_16x16x32_bf16 v[42:45], v[214:217], v[198:201], v[42:45]
	ds_read_b128 v[210:213], v169 offset:45056
	ds_read_b128 v[214:217], v169 offset:47104
	v_mfma_f32_16x16x32_bf16 v[86:89], v[218:221], v[186:189], v[86:89]
	v_mfma_f32_16x16x32_bf16 v[94:97], v[218:221], v[190:193], v[94:97]
	v_mfma_f32_16x16x32_bf16 v[102:105], v[218:221], v[194:197], v[102:105]
	v_mfma_f32_16x16x32_bf16 v[46:49], v[218:221], v[198:201], v[46:49]
	s_waitcnt lgkmcnt(0)
	v_mfma_f32_16x16x32_bf16 v[114:117], v[202:205], v[186:189], v[114:117]
	ds_read_b128 v[218:221], v170 offset:32768
	ds_read_b128 v[222:225], v170 offset:34816
	v_mfma_f32_16x16x32_bf16 v[122:125], v[202:205], v[190:193], v[122:125]
	v_mfma_f32_16x16x32_bf16 v[132:135], v[202:205], v[194:197], v[132:135]
	v_mfma_f32_16x16x32_bf16 v[74:77], v[202:205], v[198:201], v[74:77]
	ds_read_b128 v[202:205], v171
	ds_read_b128 v[226:229], v171 offset:2048
	ds_read_b128 v[230:233], v171 offset:4096
	ds_read_b128 v[234:237], v171 offset:6144
	v_mfma_f32_16x16x32_bf16 v[118:121], v[206:209], v[186:189], v[118:121]
	v_mfma_f32_16x16x32_bf16 v[126:129], v[206:209], v[190:193], v[126:129]
	v_mfma_f32_16x16x32_bf16 v[136:139], v[206:209], v[194:197], v[136:139]
	v_mfma_f32_16x16x32_bf16 v[78:81], v[206:209], v[198:201], v[78:81]
	v_mfma_f32_16x16x32_bf16 v[110:113], v[210:213], v[186:189], v[110:113]
	v_mfma_f32_16x16x32_bf16 v[18:21], v[214:217], v[186:189], v[18:21]
	v_mfma_f32_16x16x32_bf16 v[178:181], v[210:213], v[190:193], v[178:181]
	v_mfma_f32_16x16x32_bf16 v[22:25], v[214:217], v[190:193], v[22:25]
	ds_read_b128 v[186:189], v170 offset:36864
	ds_read_b128 v[190:193], v170 offset:38912
	v_mfma_f32_16x16x32_bf16 v[26:29], v[214:217], v[194:197], v[26:29]
	v_mfma_f32_16x16x32_bf16 v[106:109], v[210:213], v[198:201], v[106:109]
	v_mfma_f32_16x16x32_bf16 v[30:33], v[214:217], v[198:201], v[30:33]
	v_mfma_f32_16x16x32_bf16 v[182:185], v[210:213], v[194:197], v[182:185]
	ds_read_b128 v[194:197], v170 offset:40960
	ds_read_b128 v[198:201], v170 offset:43008
	s_waitcnt lgkmcnt(0)
	v_mfma_f32_16x16x32_bf16 v[50:53], v[218:221], v[202:205], v[50:53]
	v_mfma_f32_16x16x32_bf16 v[54:57], v[222:225], v[202:205], v[54:57]
	v_mfma_f32_16x16x32_bf16 v[58:61], v[218:221], v[226:229], v[58:61]
	v_mfma_f32_16x16x32_bf16 v[62:65], v[222:225], v[226:229], v[62:65]
	v_mfma_f32_16x16x32_bf16 v[66:69], v[218:221], v[230:233], v[66:69]
	v_mfma_f32_16x16x32_bf16 v[70:73], v[222:225], v[230:233], v[70:73]
	v_mfma_f32_16x16x32_bf16 v[34:37], v[218:221], v[234:237], v[34:37]
	v_mfma_f32_16x16x32_bf16 v[38:41], v[222:225], v[234:237], v[38:41]
	v_mfma_f32_16x16x32_bf16 v[82:85], v[186:189], v[202:205], v[82:85]
	v_mfma_f32_16x16x32_bf16 v[90:93], v[186:189], v[226:229], v[90:93]
	v_mfma_f32_16x16x32_bf16 v[98:101], v[186:189], v[230:233], v[98:101]
	v_mfma_f32_16x16x32_bf16 v[42:45], v[186:189], v[234:237], v[42:45]
	ds_read_b128 v[186:189], v170 offset:45056
	ds_read_b128 v[206:209], v170 offset:47104
	v_mfma_f32_16x16x32_bf16 v[86:89], v[190:193], v[202:205], v[86:89]
	v_mfma_f32_16x16x32_bf16 v[94:97], v[190:193], v[226:229], v[94:97]
	v_mfma_f32_16x16x32_bf16 v[102:105], v[190:193], v[230:233], v[102:105]
	v_mfma_f32_16x16x32_bf16 v[46:49], v[190:193], v[234:237], v[46:49]
	v_mfma_f32_16x16x32_bf16 v[114:117], v[194:197], v[202:205], v[114:117]
	v_mfma_f32_16x16x32_bf16 v[118:121], v[198:201], v[202:205], v[118:121]
	v_mfma_f32_16x16x32_bf16 v[122:125], v[194:197], v[226:229], v[122:125]
	v_mfma_f32_16x16x32_bf16 v[126:129], v[198:201], v[226:229], v[126:129]
	v_mfma_f32_16x16x32_bf16 v[132:135], v[194:197], v[230:233], v[132:135]
	v_mfma_f32_16x16x32_bf16 v[136:139], v[198:201], v[230:233], v[136:139]
	v_mfma_f32_16x16x32_bf16 v[74:77], v[194:197], v[234:237], v[74:77]
	v_mfma_f32_16x16x32_bf16 v[78:81], v[198:201], v[234:237], v[78:81]
	s_mov_b32 m0, s44
	s_waitcnt vmcnt(0)
	s_barrier
; template <bool SWAP, class Epi, bool THIN = false> ...
;     ...
;     for (int st = 0; st < ns; ++st) {
;       asm volatile("s_waitcnt vmcnt(0)" ::: "memory");
;       __builtin_amdgcn_s_barrier();
;       asm volatile("" ::: "memory");
;       if (st + 1 < ns) {
;         char* nb = smem + ((st + 1) & 1) * 65536;
;         const int ko = (st + 1) * 64;
; #pragma unroll
;         for (int i = 0; i < 4; ++i) { GLDS16(A + (size_t)(ap[i] + ko), nb + tid * 16 + i * 8192); GLDS16(Bt + (size_t)(bp[i] + ko), nb + 32768 + tid * 16 + i * 8192); }
;       }
;       const char* sa = smem + (st & 1) * 65536 + (wr * 64 + fr) * 128;
;       const char* sb = smem + (st & 1) * 65536 + 32768 + (wc * 128 + fr) * 128;
;       if constexpr (THIN) {
;         if (wc == 0) {
; #pragma unroll
;           for (int ks = 0; ks < 2; ++ks) {
;             bf16x8 af[4], bf[2];
; #pragma unroll
;             for (int m = 0; m < 4; ++m) af[m] = *(const bf16x8*)(sa + m * 2048 + (((ks * 4 + fq) ^ swz) << 4));
; #pragma unroll
;             for (int n = 0; n < 2; ++n) bf[n] = *(const bf16x8*)(sb + n * 2048 + (((ks * 4 + fq) ^ swz) << 4));
; #pragma unroll
;             for (int m = 0; m < 4; ++m)
; #pragma unroll
;               for (int n = 0; n < 2; ++n)
;                 acc[m][n] = SWAP ? __builtin_amdgcn_mfma_f32_16x16x32_bf16(bf[n], af[m], acc[m][n], 0, 0, 0)
;                                  : __builtin_amdgcn_mfma_f32_16x16x32_bf16(af[m], bf[n], acc[m][n], 0, 0, 0);
;           }
;         }
;       } else {
;       bf16x8 afA[4], afB[4], bfb[2][2];
; #pragma unroll
;       for (int m = 0; m < 4; ++m) afA[m] = *(const bf16x8*)(sa + m * 2048 + ((fq ^ swz) << 4));
; #pragma unroll
;       for (int n = 0; n < 2; ++n) bfb[0][n] = *(const bf16x8*)(sb + n * 2048 + ((fq ^ swz) << 4));
; #pragma unroll
;       for (int gq = 0; gq < 8; ++gq) {
;         const int ks = gq >> 2, nh = gq & 3;
;         if (gq < 7) {
;           const int ks2 = (gq + 1) >> 2, nh2 = (gq + 1) & 3;
; #pragma unroll
;           for (int n = 0; n < 2; ++n) bfb[(gq + 1) & 1][n] = *(const bf16x8*)(sb + (nh2 * 2 + n) * 2048 + (((ks2 * 4 + fq) ^ swz) << 4));
;         }
;         if (gq == 3) {
; #pragma unroll
;           for (int m = 0; m < 4; ++m) afB[m] = *(const bf16x8*)(sa + m * 2048 + (((4 + fq) ^ swz) << 4));
;         }
;         __builtin_amdgcn_sched_barrier(0);
; #pragma unroll
	v_lshl_add_u64 v[190:191], v[2:3], 0, s[36:37]
	global_load_lds_dwordx4 v[190:191], off
	v_lshl_add_u64 v[190:191], v[4:5], 0, s[36:37]
	s_mov_b32 m0, s14
	s_waitcnt lgkmcnt(0)
	v_mfma_f32_16x16x32_bf16 v[110:113], v[186:189], v[202:205], v[110:113]
	global_load_lds_dwordx4 v[190:191], off
	v_lshl_add_u64 v[190:191], v[6:7], 0, s[36:37]
	s_mov_b32 m0, s15
	v_mfma_f32_16x16x32_bf16 v[18:21], v[206:209], v[202:205], v[18:21]
	global_load_lds_dwordx4 v[190:191], off
	v_lshl_add_u64 v[190:191], v[8:9], 0, s[36:37]
	s_mov_b32 m0, s16
	v_mfma_f32_16x16x32_bf16 v[178:181], v[186:189], v[226:229], v[178:181]
	global_load_lds_dwordx4 v[190:191], off
	v_lshl_add_u64 v[190:191], v[10:11], 0, s[36:37]
	s_mov_b32 m0, s17
	v_mfma_f32_16x16x32_bf16 v[182:185], v[186:189], v[230:233], v[182:185]
	global_load_lds_dwordx4 v[190:191], off
	v_lshl_add_u64 v[190:191], v[12:13], 0, s[36:37]
	s_mov_b32 m0, s18
	v_mfma_f32_16x16x32_bf16 v[106:109], v[186:189], v[234:237], v[106:109]
	global_load_lds_dwordx4 v[190:191], off
	v_lshl_add_u64 v[190:191], v[14:15], 0, s[36:37]
	s_mov_b32 m0, s19
	v_mfma_f32_16x16x32_bf16 v[22:25], v[206:209], v[226:229], v[22:25]
	global_load_lds_dwordx4 v[190:191], off
	v_lshl_add_u64 v[190:191], v[16:17], 0, s[36:37]
	s_mov_b32 m0, s45
	v_mfma_f32_16x16x32_bf16 v[26:29], v[206:209], v[230:233], v[26:29]
	global_load_lds_dwordx4 v[190:191], off
	ds_read_b128 v[186:189], v172
	ds_read_b128 v[190:193], v172 offset:2048
	ds_read_b128 v[194:197], v172 offset:4096
	ds_read_b128 v[198:201], v172 offset:6144
	ds_read_b128 v[202:205], v173
	ds_read_b128 v[210:213], v173 offset:2048
	ds_read_b128 v[214:217], v173 offset:4096
	ds_read_b128 v[218:221], v173 offset:6144
	v_mfma_f32_16x16x32_bf16 v[30:33], v[206:209], v[234:237], v[30:33]
	s_waitcnt lgkmcnt(0)
	v_mfma_f32_16x16x32_bf16 v[50:53], v[202:205], v[186:189], v[50:53]
	v_mfma_f32_16x16x32_bf16 v[58:61], v[202:205], v[190:193], v[58:61]
	v_mfma_f32_16x16x32_bf16 v[66:69], v[202:205], v[194:197], v[66:69]
	v_mfma_f32_16x16x32_bf16 v[34:37], v[202:205], v[198:201], v[34:37]
	ds_read_b128 v[202:205], v173 offset:8192
	ds_read_b128 v[206:209], v173 offset:10240
	v_mfma_f32_16x16x32_bf16 v[54:57], v[210:213], v[186:189], v[54:57]
	v_mfma_f32_16x16x32_bf16 v[62:65], v[210:213], v[190:193], v[62:65]
	v_mfma_f32_16x16x32_bf16 v[70:73], v[210:213], v[194:197], v[70:73]
	v_mfma_f32_16x16x32_bf16 v[38:41], v[210:213], v[198:201], v[38:41]
	v_mfma_f32_16x16x32_bf16 v[82:85], v[214:217], v[186:189], v[82:85]
	v_mfma_f32_16x16x32_bf16 v[90:93], v[214:217], v[190:193], v[90:93]
	v_mfma_f32_16x16x32_bf16 v[98:101], v[214:217], v[194:197], v[98:101]
	v_mfma_f32_16x16x32_bf16 v[42:45], v[214:217], v[198:201], v[42:45]
	ds_read_b128 v[210:213], v173 offset:12288
	ds_read_b128 v[214:217], v173 offset:14336
	v_mfma_f32_16x16x32_bf16 v[86:89], v[218:221], v[186:189], v[86:89]
	v_mfma_f32_16x16x32_bf16 v[94:97], v[218:221], v[190:193], v[94:97]
	v_mfma_f32_16x16x32_bf16 v[102:105], v[218:221], v[194:197], v[102:105]
	v_mfma_f32_16x16x32_bf16 v[46:49], v[218:221], v[198:201], v[46:49]
	s_waitcnt lgkmcnt(0)
	v_mfma_f32_16x16x32_bf16 v[114:117], v[202:205], v[186:189], v[114:117]
	ds_read_b128 v[218:221], v174
	ds_read_b128 v[222:225], v174 offset:2048
	v_mfma_f32_16x16x32_bf16 v[122:125], v[202:205], v[190:193], v[122:125]
	v_mfma_f32_16x16x32_bf16 v[132:135], v[202:205], v[194:197], v[132:135]
	v_mfma_f32_16x16x32_bf16 v[74:77], v[202:205], v[198:201], v[74:77]
	ds_read_b128 v[202:205], v175
	ds_read_b128 v[226:229], v175 offset:2048
	ds_read_b128 v[230:233], v175 offset:4096
	ds_read_b128 v[234:237], v175 offset:6144
	v_mfma_f32_16x16x32_bf16 v[118:121], v[206:209], v[186:189], v[118:121]
	v_mfma_f32_16x16x32_bf16 v[126:129], v[206:209], v[190:193], v[126:129]
	v_mfma_f32_16x16x32_bf16 v[136:139], v[206:209], v[194:197], v[136:139]
	v_mfma_f32_16x16x32_bf16 v[78:81], v[206:209], v[198:201], v[78:81]
	v_mfma_f32_16x16x32_bf16 v[110:113], v[210:213], v[186:189], v[110:113]
	v_mfma_f32_16x16x32_bf16 v[18:21], v[214:217], v[186:189], v[18:21]
	v_mfma_f32_16x16x32_bf16 v[178:181], v[210:213], v[190:193], v[178:181]
	v_mfma_f32_16x16x32_bf16 v[22:25], v[214:217], v[190:193], v[22:25]
	ds_read_b128 v[186:189], v174 offset:4096
	ds_read_b128 v[190:193], v174 offset:6144
	v_mfma_f32_16x16x32_bf16 v[26:29], v[214:217], v[194:197], v[26:29]
	v_mfma_f32_16x16x32_bf16 v[106:109], v[210:213], v[198:201], v[106:109]
	v_mfma_f32_16x16x32_bf16 v[30:33], v[214:217], v[198:201], v[30:33]
	v_mfma_f32_16x16x32_bf16 v[182:185], v[210:213], v[194:197], v[182:185]
	ds_read_b128 v[194:197], v174 offset:8192
	ds_read_b128 v[198:201], v174 offset:10240
	s_waitcnt lgkmcnt(0)
	v_mfma_f32_16x16x32_bf16 v[50:53], v[218:221], v[202:205], v[50:53]
	v_mfma_f32_16x16x32_bf16 v[54:57], v[222:225], v[202:205], v[54:57]
	v_mfma_f32_16x16x32_bf16 v[58:61], v[218:221], v[226:229], v[58:61]
	v_mfma_f32_16x16x32_bf16 v[62:65], v[222:225], v[226:229], v[62:65]
	v_mfma_f32_16x16x32_bf16 v[66:69], v[218:221], v[230:233], v[66:69]
	v_mfma_f32_16x16x32_bf16 v[70:73], v[222:225], v[230:233], v[70:73]
	v_mfma_f32_16x16x32_bf16 v[34:37], v[218:221], v[234:237], v[34:37]
	v_mfma_f32_16x16x32_bf16 v[38:41], v[222:225], v[234:237], v[38:41]
	v_mfma_f32_16x16x32_bf16 v[82:85], v[186:189], v[202:205], v[82:85]
	v_mfma_f32_16x16x32_bf16 v[90:93], v[186:189], v[226:229], v[90:93]
	v_mfma_f32_16x16x32_bf16 v[98:101], v[186:189], v[230:233], v[98:101]
	v_mfma_f32_16x16x32_bf16 v[42:45], v[186:189], v[234:237], v[42:45]
	ds_read_b128 v[186:189], v174 offset:12288
	ds_read_b128 v[206:209], v174 offset:14336
	v_mfma_f32_16x16x32_bf16 v[86:89], v[190:193], v[202:205], v[86:89]
	v_mfma_f32_16x16x32_bf16 v[94:97], v[190:193], v[226:229], v[94:97]
	v_mfma_f32_16x16x32_bf16 v[102:105], v[190:193], v[230:233], v[102:105]
	v_mfma_f32_16x16x32_bf16 v[46:49], v[190:193], v[234:237], v[46:49]
	v_mfma_f32_16x16x32_bf16 v[114:117], v[194:197], v[202:205], v[114:117]
	v_mfma_f32_16x16x32_bf16 v[118:121], v[198:201], v[202:205], v[118:121]
	v_mfma_f32_16x16x32_bf16 v[122:125], v[194:197], v[226:229], v[122:125]
	v_mfma_f32_16x16x32_bf16 v[126:129], v[198:201], v[226:229], v[126:129]
	v_mfma_f32_16x16x32_bf16 v[132:135], v[194:197], v[230:233], v[132:135]
	v_mfma_f32_16x16x32_bf16 v[136:139], v[198:201], v[230:233], v[136:139]
	v_mfma_f32_16x16x32_bf16 v[74:77], v[194:197], v[234:237], v[74:77]
	v_mfma_f32_16x16x32_bf16 v[78:81], v[198:201], v[234:237], v[78:81]
	s_mov_b32 m0, s13
	s_waitcnt vmcnt(0)
	s_barrier
; template <bool SWAP, class Epi, bool THIN = false> ...
;     ...
;     for (int st = 0; st < ns; ++st) {
;       asm volatile("s_waitcnt vmcnt(0)" ::: "memory");
;       __builtin_amdgcn_s_barrier();
;       asm volatile("" ::: "memory");
;       if (st + 1 < ns) {
;         char* nb = smem + ((st + 1) & 1) * 65536;
;         const int ko = (st + 1) * 64;
; #pragma unroll
;         for (int i = 0; i < 4; ++i) { GLDS16(A + (size_t)(ap[i] + ko), nb + tid * 16 + i * 8192); GLDS16(Bt + (size_t)(bp[i] + ko), nb + 32768 + tid * 16 + i * 8192); }
;       }
;       const char* sa = smem + (st & 1) * 65536 + (wr * 64 + fr) * 128;
;       const char* sb = smem + (st & 1) * 65536 + 32768 + (wc * 128 + fr) * 128;
;       if constexpr (THIN) {
;         if (wc == 0) {
; #pragma unroll
;           for (int ks = 0; ks < 2; ++ks) {
;             bf16x8 af[4], bf[2];
; #pragma unroll
;             for (int m = 0; m < 4; ++m) af[m] = *(const bf16x8*)(sa + m * 2048 + (((ks * 4 + fq) ^ swz) << 4));
; #pragma unroll
;             for (int n = 0; n < 2; ++n) bf[n] = *(const bf16x8*)(sb + n * 2048 + (((ks * 4 + fq) ^ swz) << 4));
; #pragma unroll
;             for (int m = 0; m < 4; ++m)
; #pragma unroll
;               for (int n = 0; n < 2; ++n)
;                 acc[m][n] = SWAP ? __builtin_amdgcn_mfma_f32_16x16x32_bf16(bf[n], af[m], acc[m][n], 0, 0, 0)
;                                  : __builtin_amdgcn_mfma_f32_16x16x32_bf16(af[m], bf[n], acc[m][n], 0, 0, 0);
;           }
;         }
;       } else {
;       bf16x8 afA[4], afB[4], bfb[2][2];
; #pragma unroll
;       for (int m = 0; m < 4; ++m) afA[m] = *(const bf16x8*)(sa + m * 2048 + ((fq ^ swz) << 4));
; #pragma unroll
;       for (int n = 0; n < 2; ++n) bfb[0][n] = *(const bf16x8*)(sb + n * 2048 + ((fq ^ swz) << 4));
; #pragma unroll
;       for (int gq = 0; gq < 8; ++gq) {
;         const int ks = gq >> 2, nh = gq & 3;
;         if (gq < 7) {
;           const int ks2 = (gq + 1) >> 2, nh2 = (gq + 1) & 3;
; #pragma unroll
;           for (int n = 0; n < 2; ++n) bfb[(gq + 1) & 1][n] = *(const bf16x8*)(sb + (nh2 * 2 + n) * 2048 + (((ks2 * 4 + fq) ^ swz) << 4));
;         }
;         if (gq == 3) {
; #pragma unroll
;           for (int m = 0; m < 4; ++m) afB[m] = *(const bf16x8*)(sa + m * 2048 + (((4 + fq) ^ swz) << 4));
;         }
;         __builtin_amdgcn_sched_barrier(0);
; #pragma unroll
	v_lshl_add_u64 v[190:191], v[2:3], 0, s[38:39]
	global_load_lds_dwordx4 v[190:191], off
	v_lshl_add_u64 v[190:191], v[4:5], 0, s[38:39]
	s_mov_b32 m0, s8
	s_waitcnt lgkmcnt(0)
	v_mfma_f32_16x16x32_bf16 v[110:113], v[186:189], v[202:205], v[110:113]
	global_load_lds_dwordx4 v[190:191], off
	v_lshl_add_u64 v[190:191], v[6:7], 0, s[38:39]
	s_mov_b32 m0, s7
	v_mfma_f32_16x16x32_bf16 v[18:21], v[206:209], v[202:205], v[18:21]
	global_load_lds_dwordx4 v[190:191], off
	v_lshl_add_u64 v[190:191], v[8:9], 0, s[38:39]
	s_mov_b32 m0, s6
	v_mfma_f32_16x16x32_bf16 v[178:181], v[186:189], v[226:229], v[178:181]
	global_load_lds_dwordx4 v[190:191], off
	v_lshl_add_u64 v[190:191], v[10:11], 0, s[38:39]
	s_mov_b32 m0, s9
	v_mfma_f32_16x16x32_bf16 v[182:185], v[186:189], v[230:233], v[182:185]
	global_load_lds_dwordx4 v[190:191], off
	v_lshl_add_u64 v[190:191], v[12:13], 0, s[38:39]
	s_mov_b32 m0, s10
	v_mfma_f32_16x16x32_bf16 v[106:109], v[186:189], v[234:237], v[106:109]
	global_load_lds_dwordx4 v[190:191], off
	v_lshl_add_u64 v[190:191], v[14:15], 0, s[38:39]
	s_mov_b32 m0, s11
	v_mfma_f32_16x16x32_bf16 v[22:25], v[206:209], v[226:229], v[22:25]
	global_load_lds_dwordx4 v[190:191], off
	v_lshl_add_u64 v[190:191], v[16:17], 0, s[38:39]
	s_mov_b32 m0, s12
	v_mfma_f32_16x16x32_bf16 v[26:29], v[206:209], v[230:233], v[26:29]
	global_load_lds_dwordx4 v[190:191], off
	ds_read_b128 v[186:189], v168
	ds_read_b128 v[190:193], v168 offset:2048
	ds_read_b128 v[194:197], v168 offset:4096
	ds_read_b128 v[198:201], v168 offset:6144
	ds_read_b128 v[202:205], v169 offset:32768
	ds_read_b128 v[210:213], v169 offset:34816
	ds_read_b128 v[214:217], v169 offset:36864
	ds_read_b128 v[218:221], v169 offset:38912
	v_mfma_f32_16x16x32_bf16 v[30:33], v[206:209], v[234:237], v[30:33]
	s_waitcnt lgkmcnt(0)
	v_mfma_f32_16x16x32_bf16 v[50:53], v[202:205], v[186:189], v[50:53]
	v_mfma_f32_16x16x32_bf16 v[58:61], v[202:205], v[190:193], v[58:61]
	v_mfma_f32_16x16x32_bf16 v[66:69], v[202:205], v[194:197], v[66:69]
	v_mfma_f32_16x16x32_bf16 v[34:37], v[202:205], v[198:201], v[34:37]
	ds_read_b128 v[202:205], v169 offset:40960
	ds_read_b128 v[206:209], v169 offset:43008
	v_mfma_f32_16x16x32_bf16 v[54:57], v[210:213], v[186:189], v[54:57]
	v_mfma_f32_16x16x32_bf16 v[62:65], v[210:213], v[190:193], v[62:65]
	v_mfma_f32_16x16x32_bf16 v[70:73], v[210:213], v[194:197], v[70:73]
	v_mfma_f32_16x16x32_bf16 v[38:41], v[210:213], v[198:201], v[38:41]
	v_mfma_f32_16x16x32_bf16 v[82:85], v[214:217], v[186:189], v[82:85]
	v_mfma_f32_16x16x32_bf16 v[90:93], v[214:217], v[190:193], v[90:93]
	v_mfma_f32_16x16x32_bf16 v[98:101], v[214:217], v[194:197], v[98:101]
	v_mfma_f32_16x16x32_bf16 v[42:45], v[214:217], v[198:201], v[42:45]
	ds_read_b128 v[210:213], v169 offset:45056
	ds_read_b128 v[214:217], v169 offset:47104
	v_mfma_f32_16x16x32_bf16 v[86:89], v[218:221], v[186:189], v[86:89]
	v_mfma_f32_16x16x32_bf16 v[94:97], v[218:221], v[190:193], v[94:97]
	v_mfma_f32_16x16x32_bf16 v[102:105], v[218:221], v[194:197], v[102:105]
	v_mfma_f32_16x16x32_bf16 v[46:49], v[218:221], v[198:201], v[46:49]
	s_waitcnt lgkmcnt(0)
	v_mfma_f32_16x16x32_bf16 v[114:117], v[202:205], v[186:189], v[114:117]
	ds_read_b128 v[218:221], v170 offset:32768
	ds_read_b128 v[222:225], v170 offset:34816
	v_mfma_f32_16x16x32_bf16 v[122:125], v[202:205], v[190:193], v[122:125]
	v_mfma_f32_16x16x32_bf16 v[132:135], v[202:205], v[194:197], v[132:135]
	v_mfma_f32_16x16x32_bf16 v[74:77], v[202:205], v[198:201], v[74:77]
	ds_read_b128 v[202:205], v171
	ds_read_b128 v[226:229], v171 offset:2048
	ds_read_b128 v[230:233], v171 offset:4096
	ds_read_b128 v[234:237], v171 offset:6144
	v_mfma_f32_16x16x32_bf16 v[118:121], v[206:209], v[186:189], v[118:121]
	v_mfma_f32_16x16x32_bf16 v[126:129], v[206:209], v[190:193], v[126:129]
	v_mfma_f32_16x16x32_bf16 v[136:139], v[206:209], v[194:197], v[136:139]
	v_mfma_f32_16x16x32_bf16 v[78:81], v[206:209], v[198:201], v[78:81]
	v_mfma_f32_16x16x32_bf16 v[110:113], v[210:213], v[186:189], v[110:113]
	v_mfma_f32_16x16x32_bf16 v[18:21], v[214:217], v[186:189], v[18:21]
	v_mfma_f32_16x16x32_bf16 v[178:181], v[210:213], v[190:193], v[178:181]
	v_mfma_f32_16x16x32_bf16 v[22:25], v[214:217], v[190:193], v[22:25]
	ds_read_b128 v[186:189], v170 offset:36864
	ds_read_b128 v[190:193], v170 offset:38912
	v_mfma_f32_16x16x32_bf16 v[26:29], v[214:217], v[194:197], v[26:29]
	v_mfma_f32_16x16x32_bf16 v[106:109], v[210:213], v[198:201], v[106:109]
	v_mfma_f32_16x16x32_bf16 v[30:33], v[214:217], v[198:201], v[30:33]
	v_mfma_f32_16x16x32_bf16 v[182:185], v[210:213], v[194:197], v[182:185]
	ds_read_b128 v[194:197], v170 offset:40960
	ds_read_b128 v[198:201], v170 offset:43008
	s_waitcnt lgkmcnt(0)
	v_mfma_f32_16x16x32_bf16 v[50:53], v[218:221], v[202:205], v[50:53]
	v_mfma_f32_16x16x32_bf16 v[54:57], v[222:225], v[202:205], v[54:57]
	v_mfma_f32_16x16x32_bf16 v[58:61], v[218:221], v[226:229], v[58:61]
	v_mfma_f32_16x16x32_bf16 v[62:65], v[222:225], v[226:229], v[62:65]
	v_mfma_f32_16x16x32_bf16 v[66:69], v[218:221], v[230:233], v[66:69]
	v_mfma_f32_16x16x32_bf16 v[70:73], v[222:225], v[230:233], v[70:73]
	v_mfma_f32_16x16x32_bf16 v[34:37], v[218:221], v[234:237], v[34:37]
	v_mfma_f32_16x16x32_bf16 v[38:41], v[222:225], v[234:237], v[38:41]
	v_mfma_f32_16x16x32_bf16 v[82:85], v[186:189], v[202:205], v[82:85]
	v_mfma_f32_16x16x32_bf16 v[90:93], v[186:189], v[226:229], v[90:93]
	v_mfma_f32_16x16x32_bf16 v[98:101], v[186:189], v[230:233], v[98:101]
	v_mfma_f32_16x16x32_bf16 v[42:45], v[186:189], v[234:237], v[42:45]
	ds_read_b128 v[186:189], v170 offset:45056
	ds_read_b128 v[206:209], v170 offset:47104
	v_mfma_f32_16x16x32_bf16 v[86:89], v[190:193], v[202:205], v[86:89]
	v_mfma_f32_16x16x32_bf16 v[94:97], v[190:193], v[226:229], v[94:97]
	v_mfma_f32_16x16x32_bf16 v[102:105], v[190:193], v[230:233], v[102:105]
	v_mfma_f32_16x16x32_bf16 v[46:49], v[190:193], v[234:237], v[46:49]
	v_mfma_f32_16x16x32_bf16 v[114:117], v[194:197], v[202:205], v[114:117]
	v_mfma_f32_16x16x32_bf16 v[118:121], v[198:201], v[202:205], v[118:121]
	v_mfma_f32_16x16x32_bf16 v[122:125], v[194:197], v[226:229], v[122:125]
	v_mfma_f32_16x16x32_bf16 v[126:129], v[198:201], v[226:229], v[126:129]
	v_mfma_f32_16x16x32_bf16 v[132:135], v[194:197], v[230:233], v[132:135]
	v_mfma_f32_16x16x32_bf16 v[136:139], v[198:201], v[230:233], v[136:139]
	v_mfma_f32_16x16x32_bf16 v[74:77], v[194:197], v[234:237], v[74:77]
	v_mfma_f32_16x16x32_bf16 v[78:81], v[198:201], v[234:237], v[78:81]
	v_readfirstlane_b32 s6, v142
	s_waitcnt vmcnt(0)
	s_barrier
; template <bool SWAP, class Epi, bool THIN = false> ...
;     ...
;     for (int st = 0; st < ns; ++st) {
;       asm volatile("s_waitcnt vmcnt(0)" ::: "memory");
;       __builtin_amdgcn_s_barrier();
;       asm volatile("" ::: "memory");
;       if (st + 1 < ns) {
;         char* nb = smem + ((st + 1) & 1) * 65536;
;         const int ko = (st + 1) * 64;
; #pragma unroll
;         for (int i = 0; i < 4; ++i) { GLDS16(A + (size_t)(ap[i] + ko), nb + tid * 16 + i * 8192); GLDS16(Bt + (size_t)(bp[i] + ko), nb + 32768 + tid * 16 + i * 8192); }
;       }
;       const char* sa = smem + (st & 1) * 65536 + (wr * 64 + fr) * 128;
;       const char* sb = smem + (st & 1) * 65536 + 32768 + (wc * 128 + fr) * 128;
;       if constexpr (THIN) {
;         if (wc == 0) {
; #pragma unroll
;           for (int ks = 0; ks < 2; ++ks) {
;             bf16x8 af[4], bf[2];
; #pragma unroll
;             for (int m = 0; m < 4; ++m) af[m] = *(const bf16x8*)(sa + m * 2048 + (((ks * 4 + fq) ^ swz) << 4));
; #pragma unroll
;             for (int n = 0; n < 2; ++n) bf[n] = *(const bf16x8*)(sb + n * 2048 + (((ks * 4 + fq) ^ swz) << 4));
; #pragma unroll
;             for (int m = 0; m < 4; ++m)
; #pragma unroll
;               for (int n = 0; n < 2; ++n)
;                 acc[m][n] = SWAP ? __builtin_amdgcn_mfma_f32_16x16x32_bf16(bf[n], af[m], acc[m][n], 0, 0, 0)
;                                  : __builtin_amdgcn_mfma_f32_16x16x32_bf16(af[m], bf[n], acc[m][n], 0, 0, 0);
;           }
;         }
;       } else {
;       bf16x8 afA[4], afB[4], bfb[2][2];
; #pragma unroll
;       for (int m = 0; m < 4; ++m) afA[m] = *(const bf16x8*)(sa + m * 2048 + ((fq ^ swz) << 4));
; #pragma unroll
;       for (int n = 0; n < 2; ++n) bfb[0][n] = *(const bf16x8*)(sb + n * 2048 + ((fq ^ swz) << 4));
; #pragma unroll
;       for (int gq = 0; gq < 8; ++gq) {
;         const int ks = gq >> 2, nh = gq & 3;
;         if (gq < 7) {
;           const int ks2 = (gq + 1) >> 2, nh2 = (gq + 1) & 3;
; #pragma unroll
;           for (int n = 0; n < 2; ++n) bfb[(gq + 1) & 1][n] = *(const bf16x8*)(sb + (nh2 * 2 + n) * 2048 + (((ks2 * 4 + fq) ^ swz) << 4));
;         }
;         if (gq == 3) {
; #pragma unroll
;           for (int m = 0; m < 4; ++m) afB[m] = *(const bf16x8*)(sa + m * 2048 + (((4 + fq) ^ swz) << 4));
;         }
;         __builtin_amdgcn_sched_barrier(0);
; #pragma unroll
	v_lshl_add_u64 v[190:191], v[2:3], 0, s[40:41]
	s_mov_b32 m0, s6
	v_readfirstlane_b32 s6, v153
	global_load_lds_dwordx4 v[190:191], off
	v_lshl_add_u64 v[190:191], v[4:5], 0, s[40:41]
	s_mov_b32 m0, s6
	v_readfirstlane_b32 s6, v154
	global_load_lds_dwordx4 v[190:191], off
	v_lshl_add_u64 v[190:191], v[6:7], 0, s[40:41]
	s_mov_b32 m0, s6
	v_readfirstlane_b32 s6, v155
	global_load_lds_dwordx4 v[190:191], off
	v_lshl_add_u64 v[190:191], v[8:9], 0, s[40:41]
	s_mov_b32 m0, s6
	v_readfirstlane_b32 s6, v156
	global_load_lds_dwordx4 v[190:191], off
	v_lshl_add_u64 v[190:191], v[10:11], 0, s[40:41]
	s_mov_b32 m0, s6
	v_readfirstlane_b32 s6, v157
	global_load_lds_dwordx4 v[190:191], off
	v_lshl_add_u64 v[190:191], v[12:13], 0, s[40:41]
	s_mov_b32 m0, s6
	v_readfirstlane_b32 s6, v158
	global_load_lds_dwordx4 v[190:191], off
	v_lshl_add_u64 v[190:191], v[14:15], 0, s[40:41]
	s_mov_b32 m0, s6
	v_readfirstlane_b32 s6, v159
	global_load_lds_dwordx4 v[190:191], off
	v_lshl_add_u64 v[190:191], v[16:17], 0, s[40:41]
	s_mov_b32 m0, s6
	s_waitcnt lgkmcnt(0)
	v_mfma_f32_16x16x32_bf16 v[110:113], v[186:189], v[202:205], v[110:113]
	global_load_lds_dwordx4 v[190:191], off
	v_mfma_f32_16x16x32_bf16 v[18:21], v[206:209], v[202:205], v[18:21]
	v_mfma_f32_16x16x32_bf16 v[178:181], v[186:189], v[226:229], v[178:181]
	v_mfma_f32_16x16x32_bf16 v[182:185], v[186:189], v[230:233], v[182:185]
	v_mfma_f32_16x16x32_bf16 v[106:109], v[186:189], v[234:237], v[106:109]
	ds_read_b128 v[186:189], v172
	ds_read_b128 v[190:193], v172 offset:2048
	ds_read_b128 v[194:197], v172 offset:4096
	ds_read_b128 v[198:201], v172 offset:6144
	ds_read_b128 v[202:205], v173
	ds_read_b128 v[210:213], v173 offset:2048
	ds_read_b128 v[214:217], v173 offset:4096
	ds_read_b128 v[218:221], v173 offset:6144
	v_mfma_f32_16x16x32_bf16 v[22:25], v[206:209], v[226:229], v[22:25]
	v_mfma_f32_16x16x32_bf16 v[26:29], v[206:209], v[230:233], v[26:29]
	v_mfma_f32_16x16x32_bf16 v[30:33], v[206:209], v[234:237], v[30:33]
	s_waitcnt lgkmcnt(0)
	v_mfma_f32_16x16x32_bf16 v[50:53], v[202:205], v[186:189], v[50:53]
	v_mfma_f32_16x16x32_bf16 v[58:61], v[202:205], v[190:193], v[58:61]
	v_mfma_f32_16x16x32_bf16 v[66:69], v[202:205], v[194:197], v[66:69]
	v_mfma_f32_16x16x32_bf16 v[34:37], v[202:205], v[198:201], v[34:37]
	ds_read_b128 v[202:205], v173 offset:8192
	ds_read_b128 v[206:209], v173 offset:10240
	v_mfma_f32_16x16x32_bf16 v[54:57], v[210:213], v[186:189], v[54:57]
	v_mfma_f32_16x16x32_bf16 v[62:65], v[210:213], v[190:193], v[62:65]
	v_mfma_f32_16x16x32_bf16 v[70:73], v[210:213], v[194:197], v[70:73]
	v_mfma_f32_16x16x32_bf16 v[38:41], v[210:213], v[198:201], v[38:41]
	v_mfma_f32_16x16x32_bf16 v[82:85], v[214:217], v[186:189], v[82:85]
	v_mfma_f32_16x16x32_bf16 v[90:93], v[214:217], v[190:193], v[90:93]
	v_mfma_f32_16x16x32_bf16 v[98:101], v[214:217], v[194:197], v[98:101]
	v_mfma_f32_16x16x32_bf16 v[42:45], v[214:217], v[198:201], v[42:45]
	ds_read_b128 v[210:213], v173 offset:12288
	ds_read_b128 v[214:217], v173 offset:14336
	v_mfma_f32_16x16x32_bf16 v[86:89], v[218:221], v[186:189], v[86:89]
	v_mfma_f32_16x16x32_bf16 v[94:97], v[218:221], v[190:193], v[94:97]
	v_mfma_f32_16x16x32_bf16 v[102:105], v[218:221], v[194:197], v[102:105]
	v_mfma_f32_16x16x32_bf16 v[46:49], v[218:221], v[198:201], v[46:49]
	s_waitcnt lgkmcnt(0)
	v_mfma_f32_16x16x32_bf16 v[114:117], v[202:205], v[186:189], v[114:117]
	ds_read_b128 v[218:221], v174
	ds_read_b128 v[222:225], v174 offset:2048
	v_mfma_f32_16x16x32_bf16 v[122:125], v[202:205], v[190:193], v[122:125]
	v_mfma_f32_16x16x32_bf16 v[132:135], v[202:205], v[194:197], v[132:135]
	v_mfma_f32_16x16x32_bf16 v[74:77], v[202:205], v[198:201], v[74:77]
	ds_read_b128 v[202:205], v175
	ds_read_b128 v[226:229], v175 offset:2048
	ds_read_b128 v[230:233], v175 offset:4096
	ds_read_b128 v[234:237], v175 offset:6144
	v_mfma_f32_16x16x32_bf16 v[118:121], v[206:209], v[186:189], v[118:121]
	v_mfma_f32_16x16x32_bf16 v[126:129], v[206:209], v[190:193], v[126:129]
	v_mfma_f32_16x16x32_bf16 v[136:139], v[206:209], v[194:197], v[136:139]
	v_mfma_f32_16x16x32_bf16 v[78:81], v[206:209], v[198:201], v[78:81]
	v_mfma_f32_16x16x32_bf16 v[110:113], v[210:213], v[186:189], v[110:113]
	v_mfma_f32_16x16x32_bf16 v[18:21], v[214:217], v[186:189], v[18:21]
	v_mfma_f32_16x16x32_bf16 v[178:181], v[210:213], v[190:193], v[178:181]
	v_mfma_f32_16x16x32_bf16 v[22:25], v[214:217], v[190:193], v[22:25]
	ds_read_b128 v[186:189], v174 offset:4096
	ds_read_b128 v[190:193], v174 offset:6144
	v_mfma_f32_16x16x32_bf16 v[26:29], v[214:217], v[194:197], v[26:29]
	v_mfma_f32_16x16x32_bf16 v[106:109], v[210:213], v[198:201], v[106:109]
	v_mfma_f32_16x16x32_bf16 v[30:33], v[214:217], v[198:201], v[30:33]
	v_mfma_f32_16x16x32_bf16 v[182:185], v[210:213], v[194:197], v[182:185]
	ds_read_b128 v[194:197], v174 offset:8192
	ds_read_b128 v[198:201], v174 offset:10240
	s_waitcnt lgkmcnt(0)
	v_mfma_f32_16x16x32_bf16 v[50:53], v[218:221], v[202:205], v[50:53]
	v_mfma_f32_16x16x32_bf16 v[54:57], v[222:225], v[202:205], v[54:57]
	v_mfma_f32_16x16x32_bf16 v[58:61], v[218:221], v[226:229], v[58:61]
	v_mfma_f32_16x16x32_bf16 v[62:65], v[222:225], v[226:229], v[62:65]
	v_mfma_f32_16x16x32_bf16 v[66:69], v[218:221], v[230:233], v[66:69]
	v_mfma_f32_16x16x32_bf16 v[70:73], v[222:225], v[230:233], v[70:73]
	v_mfma_f32_16x16x32_bf16 v[34:37], v[218:221], v[234:237], v[34:37]
	v_mfma_f32_16x16x32_bf16 v[38:41], v[222:225], v[234:237], v[38:41]
	v_mfma_f32_16x16x32_bf16 v[82:85], v[186:189], v[202:205], v[82:85]
	v_mfma_f32_16x16x32_bf16 v[90:93], v[186:189], v[226:229], v[90:93]
	v_mfma_f32_16x16x32_bf16 v[98:101], v[186:189], v[230:233], v[98:101]
	v_mfma_f32_16x16x32_bf16 v[42:45], v[186:189], v[234:237], v[42:45]
	ds_read_b128 v[186:189], v174 offset:12288
	ds_read_b128 v[206:209], v174 offset:14336
	v_mfma_f32_16x16x32_bf16 v[86:89], v[190:193], v[202:205], v[86:89]
	v_mfma_f32_16x16x32_bf16 v[94:97], v[190:193], v[226:229], v[94:97]
	v_mfma_f32_16x16x32_bf16 v[102:105], v[190:193], v[230:233], v[102:105]
	v_mfma_f32_16x16x32_bf16 v[46:49], v[190:193], v[234:237], v[46:49]
	v_mfma_f32_16x16x32_bf16 v[114:117], v[194:197], v[202:205], v[114:117]
	v_mfma_f32_16x16x32_bf16 v[118:121], v[198:201], v[202:205], v[118:121]
	v_mfma_f32_16x16x32_bf16 v[122:125], v[194:197], v[226:229], v[122:125]
	v_mfma_f32_16x16x32_bf16 v[126:129], v[198:201], v[226:229], v[126:129]
	v_mfma_f32_16x16x32_bf16 v[132:135], v[194:197], v[230:233], v[132:135]
	v_mfma_f32_16x16x32_bf16 v[136:139], v[198:201], v[230:233], v[136:139]
	v_mfma_f32_16x16x32_bf16 v[74:77], v[194:197], v[234:237], v[74:77]
	v_mfma_f32_16x16x32_bf16 v[78:81], v[198:201], v[234:237], v[78:81]
	v_readfirstlane_b32 s6, v160
	s_waitcnt vmcnt(0)
	s_barrier
; template <bool SWAP, class Epi, bool THIN = false> ...
;     ...
;     for (int st = 0; st < ns; ++st) {
;       asm volatile("s_waitcnt vmcnt(0)" ::: "memory");
;       __builtin_amdgcn_s_barrier();
;       asm volatile("" ::: "memory");
;       if (st + 1 < ns) {
;         char* nb = smem + ((st + 1) & 1) * 65536;
;         const int ko = (st + 1) * 64;
; #pragma unroll
;         for (int i = 0; i < 4; ++i) { GLDS16(A + (size_t)(ap[i] + ko), nb + tid * 16 + i * 8192); GLDS16(Bt + (size_t)(bp[i] + ko), nb + 32768 + tid * 16 + i * 8192); }
;       }
;       const char* sa = smem + (st & 1) * 65536 + (wr * 64 + fr) * 128;
;       const char* sb = smem + (st & 1) * 65536 + 32768 + (wc * 128 + fr) * 128;
;       if constexpr (THIN) {
;         if (wc == 0) {
; #pragma unroll
;           for (int ks = 0; ks < 2; ++ks) {
;             bf16x8 af[4], bf[2];
; #pragma unroll
;             for (int m = 0; m < 4; ++m) af[m] = *(const bf16x8*)(sa + m * 2048 + (((ks * 4 + fq) ^ swz) << 4));
; #pragma unroll
;             for (int n = 0; n < 2; ++n) bf[n] = *(const bf16x8*)(sb + n * 2048 + (((ks * 4 + fq) ^ swz) << 4));
; #pragma unroll
;             for (int m = 0; m < 4; ++m)
; #pragma unroll
;               for (int n = 0; n < 2; ++n)
;                 acc[m][n] = SWAP ? __builtin_amdgcn_mfma_f32_16x16x32_bf16(bf[n], af[m], acc[m][n], 0, 0, 0)
;                                  : __builtin_amdgcn_mfma_f32_16x16x32_bf16(af[m], bf[n], acc[m][n], 0, 0, 0);
;           }
;         }
;       } else {
;       bf16x8 afA[4], afB[4], bfb[2][2];
; #pragma unroll
;       for (int m = 0; m < 4; ++m) afA[m] = *(const bf16x8*)(sa + m * 2048 + ((fq ^ swz) << 4));
; #pragma unroll
;       for (int n = 0; n < 2; ++n) bfb[0][n] = *(const bf16x8*)(sb + n * 2048 + ((fq ^ swz) << 4));
; #pragma unroll
;       for (int gq = 0; gq < 8; ++gq) {
;         const int ks = gq >> 2, nh = gq & 3;
;         if (gq < 7) {
;           const int ks2 = (gq + 1) >> 2, nh2 = (gq + 1) & 3;
; #pragma unroll
;           for (int n = 0; n < 2; ++n) bfb[(gq + 1) & 1][n] = *(const bf16x8*)(sb + (nh2 * 2 + n) * 2048 + (((ks2 * 4 + fq) ^ swz) << 4));
;         }
;         if (gq == 3) {
; #pragma unroll
;           for (int m = 0; m < 4; ++m) afB[m] = *(const bf16x8*)(sa + m * 2048 + (((4 + fq) ^ swz) << 4));
;         }
;         __builtin_amdgcn_sched_barrier(0);
; #pragma unroll
	v_lshl_add_u64 v[2:3], v[2:3], 0, s[42:43]
	s_mov_b32 m0, s6
	v_readfirstlane_b32 s6, v161
	global_load_lds_dwordx4 v[2:3], off
	v_lshl_add_u64 v[190:191], v[4:5], 0, s[42:43]
	s_mov_b32 m0, s6
	v_readfirstlane_b32 s6, v162
	global_load_lds_dwordx4 v[190:191], off
	v_lshl_add_u64 v[6:7], v[6:7], 0, s[42:43]
	s_mov_b32 m0, s6
	v_readfirstlane_b32 s6, v163
	global_load_lds_dwordx4 v[6:7], off
	v_lshl_add_u64 v[6:7], v[8:9], 0, s[42:43]
	s_mov_b32 m0, s6
	v_readfirstlane_b32 s6, v164
	global_load_lds_dwordx4 v[6:7], off
	v_lshl_add_u64 v[6:7], v[10:11], 0, s[42:43]
	s_mov_b32 m0, s6
	v_readfirstlane_b32 s6, v165
	global_load_lds_dwordx4 v[6:7], off
	v_lshl_add_u64 v[6:7], v[12:13], 0, s[42:43]
	s_mov_b32 m0, s6
	v_readfirstlane_b32 s6, v166
	global_load_lds_dwordx4 v[6:7], off
	v_lshl_add_u64 v[6:7], v[14:15], 0, s[42:43]
	s_mov_b32 m0, s6
	v_readfirstlane_b32 s6, v167
	global_load_lds_dwordx4 v[6:7], off
	v_lshl_add_u64 v[6:7], v[16:17], 0, s[42:43]
	s_mov_b32 m0, s6
	s_waitcnt lgkmcnt(0)
	v_mfma_f32_16x16x32_bf16 v[110:113], v[186:189], v[202:205], v[110:113]
	global_load_lds_dwordx4 v[6:7], off
	v_mfma_f32_16x16x32_bf16 v[178:181], v[186:189], v[226:229], v[178:181]
	v_mfma_f32_16x16x32_bf16 v[2:5], v[186:189], v[230:233], v[182:185]
	v_mfma_f32_16x16x32_bf16 v[6:9], v[186:189], v[234:237], v[106:109]
	ds_read_b128 v[10:13], v168
	ds_read_b128 v[14:17], v168 offset:2048
	s_nop 0
	ds_read_b128 v[106:109], v168 offset:4096
	ds_read_b128 v[182:185], v168 offset:6144
	ds_read_b128 v[186:189], v169 offset:32768
	ds_read_b128 v[190:193], v169 offset:34816
	ds_read_b128 v[194:197], v169 offset:36864
	ds_read_b128 v[198:201], v169 offset:38912
	v_mfma_f32_16x16x32_bf16 v[18:21], v[206:209], v[202:205], v[18:21]
	v_mfma_f32_16x16x32_bf16 v[22:25], v[206:209], v[226:229], v[22:25]
	v_mfma_f32_16x16x32_bf16 v[26:29], v[206:209], v[230:233], v[26:29]
	v_mfma_f32_16x16x32_bf16 v[30:33], v[206:209], v[234:237], v[30:33]
	s_waitcnt lgkmcnt(0)
	v_mfma_f32_16x16x32_bf16 v[50:53], v[186:189], v[10:13], v[50:53]
	v_mfma_f32_16x16x32_bf16 v[58:61], v[186:189], v[14:17], v[58:61]
	v_mfma_f32_16x16x32_bf16 v[66:69], v[186:189], v[106:109], v[66:69]
	v_mfma_f32_16x16x32_bf16 v[34:37], v[186:189], v[182:185], v[34:37]
	ds_read_b128 v[186:189], v169 offset:40960
	ds_read_b128 v[202:205], v169 offset:43008
	v_mfma_f32_16x16x32_bf16 v[54:57], v[190:193], v[10:13], v[54:57]
	v_mfma_f32_16x16x32_bf16 v[62:65], v[190:193], v[14:17], v[62:65]
	v_mfma_f32_16x16x32_bf16 v[70:73], v[190:193], v[106:109], v[70:73]
	v_mfma_f32_16x16x32_bf16 v[38:41], v[190:193], v[182:185], v[38:41]
	v_mfma_f32_16x16x32_bf16 v[82:85], v[194:197], v[10:13], v[82:85]
	v_mfma_f32_16x16x32_bf16 v[90:93], v[194:197], v[14:17], v[90:93]
	v_mfma_f32_16x16x32_bf16 v[98:101], v[194:197], v[106:109], v[98:101]
	v_mfma_f32_16x16x32_bf16 v[42:45], v[194:197], v[182:185], v[42:45]
	ds_read_b128 v[190:193], v169 offset:45056
	ds_read_b128 v[194:197], v169 offset:47104
	v_mfma_f32_16x16x32_bf16 v[86:89], v[198:201], v[10:13], v[86:89]
	v_mfma_f32_16x16x32_bf16 v[94:97], v[198:201], v[14:17], v[94:97]
	v_mfma_f32_16x16x32_bf16 v[102:105], v[198:201], v[106:109], v[102:105]
	v_mfma_f32_16x16x32_bf16 v[46:49], v[198:201], v[182:185], v[46:49]
	s_waitcnt lgkmcnt(0)
	v_mfma_f32_16x16x32_bf16 v[114:117], v[186:189], v[10:13], v[114:117]
	ds_read_b128 v[198:201], v170 offset:32768
	ds_read_b128 v[206:209], v170 offset:34816
	v_mfma_f32_16x16x32_bf16 v[122:125], v[186:189], v[14:17], v[122:125]
	v_mfma_f32_16x16x32_bf16 v[132:135], v[186:189], v[106:109], v[132:135]
	v_mfma_f32_16x16x32_bf16 v[74:77], v[186:189], v[182:185], v[74:77]
	ds_read_b128 v[186:189], v171
	ds_read_b128 v[210:213], v171 offset:2048
	ds_read_b128 v[214:217], v171 offset:4096
	ds_read_b128 v[218:221], v171 offset:6144
	v_mfma_f32_16x16x32_bf16 v[118:121], v[202:205], v[10:13], v[118:121]
	v_mfma_f32_16x16x32_bf16 v[126:129], v[202:205], v[14:17], v[126:129]
	v_mfma_f32_16x16x32_bf16 v[136:139], v[202:205], v[106:109], v[136:139]
	v_mfma_f32_16x16x32_bf16 v[78:81], v[202:205], v[182:185], v[78:81]
	v_mfma_f32_16x16x32_bf16 v[110:113], v[190:193], v[10:13], v[110:113]
	v_mfma_f32_16x16x32_bf16 v[10:13], v[194:197], v[10:13], v[18:21]
	v_mfma_f32_16x16x32_bf16 v[18:21], v[190:193], v[14:17], v[178:181]
	v_mfma_f32_16x16x32_bf16 v[14:17], v[194:197], v[14:17], v[22:25]
	v_mfma_f32_16x16x32_bf16 v[2:5], v[190:193], v[106:109], v[2:5]
	v_mfma_f32_16x16x32_bf16 v[22:25], v[194:197], v[106:109], v[26:29]
	s_nop 2
	ds_read_b128 v[26:29], v170 offset:36864
	ds_read_b128 v[106:109], v170 offset:38912
	v_mfma_f32_16x16x32_bf16 v[6:9], v[190:193], v[182:185], v[6:9]
	v_mfma_f32_16x16x32_bf16 v[30:33], v[194:197], v[182:185], v[30:33]
	ds_read_b128 v[178:181], v170 offset:40960
	ds_read_b128 v[182:185], v170 offset:43008
	s_waitcnt lgkmcnt(0)
	v_mfma_f32_16x16x32_bf16 v[50:53], v[198:201], v[186:189], v[50:53]
	v_mfma_f32_16x16x32_bf16 v[54:57], v[206:209], v[186:189], v[54:57]
	v_mfma_f32_16x16x32_bf16 v[58:61], v[198:201], v[210:213], v[58:61]
	v_mfma_f32_16x16x32_bf16 v[62:65], v[206:209], v[210:213], v[62:65]
	v_mfma_f32_16x16x32_bf16 v[66:69], v[198:201], v[214:217], v[66:69]
	v_mfma_f32_16x16x32_bf16 v[70:73], v[206:209], v[214:217], v[70:73]
	v_mfma_f32_16x16x32_bf16 v[34:37], v[198:201], v[218:221], v[34:37]
	v_mfma_f32_16x16x32_bf16 v[38:41], v[206:209], v[218:221], v[38:41]
	v_mfma_f32_16x16x32_bf16 v[82:85], v[26:29], v[186:189], v[82:85]
	v_mfma_f32_16x16x32_bf16 v[90:93], v[26:29], v[210:213], v[90:93]
	v_mfma_f32_16x16x32_bf16 v[98:101], v[26:29], v[214:217], v[98:101]
	v_mfma_f32_16x16x32_bf16 v[26:29], v[26:29], v[218:221], v[42:45]
	s_nop 2
	ds_read_b128 v[42:45], v170 offset:45056
	ds_read_b128 v[190:193], v170 offset:47104
	v_mfma_f32_16x16x32_bf16 v[86:89], v[106:109], v[186:189], v[86:89]
	v_mfma_f32_16x16x32_bf16 v[94:97], v[106:109], v[210:213], v[94:97]
	v_mfma_f32_16x16x32_bf16 v[102:105], v[106:109], v[214:217], v[102:105]
	v_mfma_f32_16x16x32_bf16 v[46:49], v[106:109], v[218:221], v[46:49]
	v_mfma_f32_16x16x32_bf16 v[106:109], v[178:181], v[186:189], v[114:117]
	v_mfma_f32_16x16x32_bf16 v[114:117], v[182:185], v[186:189], v[118:121]
	v_mfma_f32_16x16x32_bf16 v[118:121], v[178:181], v[210:213], v[122:125]
	v_mfma_f32_16x16x32_bf16 v[122:125], v[182:185], v[210:213], v[126:129]
	v_mfma_f32_16x16x32_bf16 v[126:129], v[178:181], v[214:217], v[132:135]
	v_mfma_f32_16x16x32_bf16 v[132:135], v[182:185], v[214:217], v[136:139]
	v_mfma_f32_16x16x32_bf16 v[74:77], v[178:181], v[218:221], v[74:77]
	v_mfma_f32_16x16x32_bf16 v[78:81], v[182:185], v[218:221], v[78:81]
	s_waitcnt vmcnt(0)
	s_barrier
; template <bool SWAP, class Epi, bool THIN = false> ...
;     ...
;     for (int st = 0; st < ns; ++st) {
;       asm volatile("s_waitcnt vmcnt(0)" ::: "memory");
;       __builtin_amdgcn_s_barrier();
;       asm volatile("" ::: "memory");
;       if (st + 1 < ns) {
;         char* nb = smem + ((st + 1) & 1) * 65536;
;         const int ko = (st + 1) * 64;
; #pragma unroll
;         for (int i = 0; i < 4; ++i) { GLDS16(A + (size_t)(ap[i] + ko), nb + tid * 16 + i * 8192); GLDS16(Bt + (size_t)(bp[i] + ko), nb + 32768 + tid * 16 + i * 8192); }
;       }
;       const char* sa = smem + (st & 1) * 65536 + (wr * 64 + fr) * 128;
;       const char* sb = smem + (st & 1) * 65536 + 32768 + (wc * 128 + fr) * 128;
;       if constexpr (THIN) {
;         if (wc == 0) {
; #pragma unroll
;           for (int ks = 0; ks < 2; ++ks) {
;             bf16x8 af[4], bf[2];
; #pragma unroll
;             for (int m = 0; m < 4; ++m) af[m] = *(const bf16x8*)(sa + m * 2048 + (((ks * 4 + fq) ^ swz) << 4));
; #pragma unroll
;             for (int n = 0; n < 2; ++n) bf[n] = *(const bf16x8*)(sb + n * 2048 + (((ks * 4 + fq) ^ swz) << 4));
; #pragma unroll
;             for (int m = 0; m < 4; ++m)
; #pragma unroll
;               for (int n = 0; n < 2; ++n)
;                 acc[m][n] = SWAP ? __builtin_amdgcn_mfma_f32_16x16x32_bf16(bf[n], af[m], acc[m][n], 0, 0, 0)
;                                  : __builtin_amdgcn_mfma_f32_16x16x32_bf16(af[m], bf[n], acc[m][n], 0, 0, 0);
;           }
;         }
;       } else {
;       bf16x8 afA[4], afB[4], bfb[2][2];
; #pragma unroll
;       for (int m = 0; m < 4; ++m) afA[m] = *(const bf16x8*)(sa + m * 2048 + ((fq ^ swz) << 4));
; #pragma unroll
;       for (int n = 0; n < 2; ++n) bfb[0][n] = *(const bf16x8*)(sb + n * 2048 + ((fq ^ swz) << 4));
; #pragma unroll
;       for (int gq = 0; gq < 8; ++gq) {
;         const int ks = gq >> 2, nh = gq & 3;
;         if (gq < 7) {
;           const int ks2 = (gq + 1) >> 2, nh2 = (gq + 1) & 3;
; #pragma unroll
;           for (int n = 0; n < 2; ++n) bfb[(gq + 1) & 1][n] = *(const bf16x8*)(sb + (nh2 * 2 + n) * 2048 + (((ks2 * 4 + fq) ^ swz) << 4));
;         }
;         if (gq == 3) {
; #pragma unroll
;           for (int m = 0; m < 4; ++m) afB[m] = *(const bf16x8*)(sa + m * 2048 + (((4 + fq) ^ swz) << 4));
;         }
;         __builtin_amdgcn_sched_barrier(0);
; #pragma unroll
	s_waitcnt lgkmcnt(0)
	v_mfma_f32_16x16x32_bf16 v[110:113], v[42:45], v[186:189], v[110:113]
	v_mfma_f32_16x16x32_bf16 v[10:13], v[190:193], v[186:189], v[10:13]
	ds_read_b128 v[136:139], v172
	ds_read_b128 v[178:181], v172 offset:2048
	ds_read_b128 v[182:185], v172 offset:4096
	ds_read_b128 v[186:189], v172 offset:6144
	v_mfma_f32_16x16x32_bf16 v[18:21], v[42:45], v[210:213], v[18:21]
	v_mfma_f32_16x16x32_bf16 v[2:5], v[42:45], v[214:217], v[2:5]
	v_mfma_f32_16x16x32_bf16 v[6:9], v[42:45], v[218:221], v[6:9]
	ds_read_b128 v[42:45], v173
	ds_read_b128 v[194:197], v173 offset:2048
	ds_read_b128 v[198:201], v173 offset:4096
	ds_read_b128 v[202:205], v173 offset:6144
	v_mfma_f32_16x16x32_bf16 v[14:17], v[190:193], v[210:213], v[14:17]
	v_mfma_f32_16x16x32_bf16 v[22:25], v[190:193], v[214:217], v[22:25]
	v_mfma_f32_16x16x32_bf16 v[30:33], v[190:193], v[218:221], v[30:33]
	s_waitcnt lgkmcnt(0)
	v_mfma_f32_16x16x32_bf16 v[50:53], v[42:45], v[136:139], v[50:53]
	v_mfma_f32_16x16x32_bf16 v[58:61], v[42:45], v[178:181], v[58:61]
	v_mfma_f32_16x16x32_bf16 v[66:69], v[42:45], v[182:185], v[66:69]
	v_mfma_f32_16x16x32_bf16 v[34:37], v[42:45], v[186:189], v[34:37]
	ds_read_b128 v[42:45], v173 offset:8192
	ds_read_b128 v[190:193], v173 offset:10240
	v_mfma_f32_16x16x32_bf16 v[54:57], v[194:197], v[136:139], v[54:57]
	v_mfma_f32_16x16x32_bf16 v[62:65], v[194:197], v[178:181], v[62:65]
	v_mfma_f32_16x16x32_bf16 v[70:73], v[194:197], v[182:185], v[70:73]
	v_mfma_f32_16x16x32_bf16 v[38:41], v[194:197], v[186:189], v[38:41]
	v_mfma_f32_16x16x32_bf16 v[82:85], v[198:201], v[136:139], v[82:85]
	v_mfma_f32_16x16x32_bf16 v[194:197], v[198:201], v[178:181], v[90:93]
	v_mfma_f32_16x16x32_bf16 v[98:101], v[198:201], v[182:185], v[98:101]
	v_mfma_f32_16x16x32_bf16 v[198:201], v[198:201], v[186:189], v[26:29]
	s_nop 2
	ds_read_b128 v[26:29], v173 offset:12288
	ds_read_b128 v[90:93], v173 offset:14336
	v_mfma_f32_16x16x32_bf16 v[86:89], v[202:205], v[136:139], v[86:89]
	v_mfma_f32_16x16x32_bf16 v[102:105], v[202:205], v[182:185], v[102:105]
	v_mfma_f32_16x16x32_bf16 v[46:49], v[202:205], v[186:189], v[46:49]
	v_mfma_f32_16x16x32_bf16 v[206:209], v[202:205], v[178:181], v[94:97]
	s_waitcnt lgkmcnt(0)
	v_mfma_f32_16x16x32_bf16 v[202:205], v[190:193], v[136:139], v[114:117]
	v_mfma_f32_16x16x32_bf16 v[210:213], v[42:45], v[178:181], v[118:121]
	s_nop 1
	ds_read_b128 v[114:117], v174
	ds_read_b128 v[118:121], v174 offset:2048
	ds_read_b128 v[226:229], v175
	ds_read_b128 v[230:233], v175 offset:2048
	ds_read_b128 v[234:237], v175 offset:4096
	ds_read_b128 v[238:241], v175 offset:6144
	v_mfma_f32_16x16x32_bf16 v[106:109], v[42:45], v[136:139], v[106:109]
	v_mfma_f32_16x16x32_bf16 v[132:135], v[190:193], v[182:185], v[132:135]
	v_mfma_f32_16x16x32_bf16 v[214:217], v[190:193], v[178:181], v[122:125]
	v_mfma_f32_16x16x32_bf16 v[218:221], v[42:45], v[182:185], v[126:129]
	v_mfma_f32_16x16x32_bf16 v[222:225], v[42:45], v[186:189], v[74:77]
	v_mfma_f32_16x16x32_bf16 v[190:193], v[190:193], v[186:189], v[78:81]
	v_mfma_f32_16x16x32_bf16 v[242:245], v[26:29], v[136:139], v[110:113]
	v_mfma_f32_16x16x32_bf16 v[136:139], v[90:93], v[136:139], v[10:13]
	v_mfma_f32_16x16x32_bf16 v[246:249], v[26:29], v[178:181], v[18:21]
	v_mfma_f32_16x16x32_bf16 v[178:181], v[90:93], v[178:181], v[14:17]
	s_nop 0
	ds_read_b128 v[10:13], v174 offset:4096
	s_nop 0
	ds_read_b128 v[14:17], v174 offset:6144
	v_mfma_f32_16x16x32_bf16 v[2:5], v[26:29], v[182:185], v[2:5]
	v_mfma_f32_16x16x32_bf16 v[6:9], v[26:29], v[186:189], v[6:9]
	v_mfma_f32_16x16x32_bf16 v[182:185], v[90:93], v[182:185], v[22:25]
	v_mfma_f32_16x16x32_bf16 v[186:189], v[90:93], v[186:189], v[30:33]
	s_waitcnt lgkmcnt(0)
	v_mfma_f32_16x16x32_bf16 v[90:93], v[118:121], v[230:233], v[62:65]
	v_mfma_f32_16x16x32_bf16 v[62:65], v[114:117], v[234:237], v[66:69]
	v_mfma_f32_16x16x32_bf16 v[30:33], v[114:117], v[238:241], v[34:37]
	s_nop 2
	ds_read_b128 v[34:37], v174 offset:8192
	ds_read_b128 v[66:69], v174 offset:10240
	v_mfma_f32_16x16x32_bf16 v[126:129], v[114:117], v[226:229], v[50:53]
	v_mfma_f32_16x16x32_bf16 v[122:125], v[118:121], v[226:229], v[54:57]
	v_mfma_f32_16x16x32_bf16 v[94:97], v[114:117], v[230:233], v[58:61]
	v_mfma_f32_16x16x32_bf16 v[58:61], v[118:121], v[234:237], v[70:73]
	v_mfma_f32_16x16x32_bf16 v[26:29], v[118:121], v[238:241], v[38:41]
	v_mfma_f32_16x16x32_bf16 v[114:117], v[14:17], v[226:229], v[86:89]
	v_mfma_f32_16x16x32_bf16 v[86:89], v[10:13], v[230:233], v[194:197]
	v_mfma_f32_16x16x32_bf16 v[22:25], v[10:13], v[238:241], v[198:201]
	s_nop 1
	ds_read_b128 v[194:197], v174 offset:12288
	ds_read_b128 v[198:201], v174 offset:14336
	v_mfma_f32_16x16x32_bf16 v[118:121], v[10:13], v[226:229], v[82:85]
	v_mfma_f32_16x16x32_bf16 v[82:85], v[14:17], v[230:233], v[206:209]
	v_mfma_f32_16x16x32_bf16 v[54:57], v[10:13], v[234:237], v[98:101]
	v_mfma_f32_16x16x32_bf16 v[50:53], v[14:17], v[234:237], v[102:105]
	v_mfma_f32_16x16x32_bf16 v[18:21], v[14:17], v[238:241], v[46:49]
	s_waitcnt lgkmcnt(0)
	v_mfma_f32_16x16x32_bf16 v[110:113], v[34:37], v[226:229], v[106:109]
	v_mfma_f32_16x16x32_bf16 v[106:109], v[66:69], v[226:229], v[202:205]
	v_mfma_f32_16x16x32_bf16 v[78:81], v[34:37], v[230:233], v[210:213]
	v_mfma_f32_16x16x32_bf16 v[74:77], v[66:69], v[230:233], v[214:217]
	v_mfma_f32_16x16x32_bf16 v[46:49], v[34:37], v[234:237], v[218:221]
	v_mfma_f32_16x16x32_bf16 v[42:45], v[66:69], v[234:237], v[132:135]
	v_mfma_f32_16x16x32_bf16 v[14:17], v[34:37], v[238:241], v[222:225]
	v_mfma_f32_16x16x32_bf16 v[10:13], v[66:69], v[238:241], v[190:193]
	v_mov_b32_e32 v130, v1
	s_waitcnt vmcnt(0)
	s_barrier
; __device__ __forceinline__ int get_tid512() { int t = threadIdx.x; asm volatile("" : "+v"(t)); return t; }
; __device__ __forceinline__ unsigned pack2(float a, float b) { unsigned r; asm("v_cvt_pk_bf16_f32 %0, %1, %2" : "=v"(r) : "v"(a), "v"(b)); return r; }
;   __device__ __forceinline__ void c4(int g, int rig, int col, f32x4 v) const {
;     const size_t row = (size_t)g * ostride + rig;
;     float s = 1.f;
;     if (NP > 0) {
;       float t = 0.f;
; #pragma unroll
;       for (int q = 0; q < NP; ++q) t += part[(size_t)q * pstride + row];
;       s = rsqrtf(t * inv_n + 1e-6f);
;     }
;     uint2 u; u.x = pack2(v[0] * s, v[1] * s); u.y = pack2(v[2] * s, v[3] * s);
;     *(uint2*)(out + row * ld + col) = u;
;   }
; template <bool SWAP, class Epi, bool THIN = false> ...
;     ...
;     const int te = get_tid512();
;     const int fr_e = te & 15, fq_e = (te & 63) >> 4, wr_e = te >> 7, wc_e = (te >> 6) & 1;
;     const int sub = 2 * mt + (wr_e >> 1);
;     const int g = sub / tpg, ti = sub - g * tpg;
;     const int rig0 = ti * step - halo;
;     const int rw = (wr_e & 1) * 64;
;     if constexpr (Epi::KIND == 0) {
; #pragma unroll
;       for (int m = 0; m < 4; ++m) {
;         const int rig = rig0 + rw + m * 16 + fr_e;
;         if constexpr (Epi::ROWSUM) {
;           float ss = 0.f;
; #pragma unroll
;           for (int n = 0; n < 8; ++n) {
;             const int col = nt * 256 + wc_e * 128 + n * 16 + fq_e * 4;
;             if (col < N) ss += epi.c4(g, rig, col, acc[m][n]);
;           }
;           ss += __shfl_xor(ss, 16); ss += __shfl_xor(ss, 32);
;           if (fq_e == 0) epi.rowsum(g, rig, nt * 2 + wc_e, ss);
;         } else {
; #pragma unroll
;           for (int n = 0; n < 8; ++n) {
;             const int col = nt * 256 + wc_e * 128 + n * 16 + fq_e * 4;
;             if (col < N) epi.c4(g, rig, col, acc[m][n]);
;           }
	v_mfma_f32_16x16x32_bf16 v[38:41], v[194:197], v[234:237], v[2:5]
	v_ashrrev_i32_e32 v34, 8, v130
	v_add_u32_e32 v34, s5, v34
	v_ashrrev_i32_e32 v35, 31, v34
	v_lshrrev_b32_e32 v35, 28, v35
	v_add_u32_e32 v35, v34, v35
	v_ashrrev_i32_e32 v134, 4, v35
	v_lshlrev_b32_e32 v35, 11, v134
	v_lshlrev_b32_e32 v34, 7, v34
	v_lshrrev_b32_e32 v3, 1, v130
	v_and_b32_e32 v132, 15, v130
	v_sub_u32_e32 v2, v34, v35
	v_and_b32_e32 v3, 64, v3
	v_mfma_f32_16x16x32_bf16 v[98:101], v[198:201], v[226:229], v[136:139]
	v_ashrrev_i32_e32 v135, 31, v134
	s_nop 1
	v_or3_b32 v136, v2, v3, v132
	v_lshlrev_b32_e32 v2, 1, v130
	v_lshrrev_b32_e32 v3, 2, v130
	v_and_b32_e32 v2, 0x80, v2
	v_and_b32_e32 v3, 12, v3
	v_mfma_f32_16x16x32_bf16 v[102:105], v[194:197], v[226:229], v[242:245]
	v_or3_b32 v132, v3, v2, s4
	v_ashrrev_i32_e32 v137, 31, v136
	v_lshlrev_b64 v[138:139], 11, v[134:135]
	v_mfma_f32_16x16x32_bf16 v[70:73], v[194:197], v[230:233], v[246:249]
	v_cmp_gt_i32_e64 s[4:5], s50, v132
	v_ashrrev_i32_e32 v133, 31, v132
	v_lshl_add_u64 v[134:135], v[138:139], 0, v[136:137]
	v_mfma_f32_16x16x32_bf16 v[66:69], v[198:201], v[230:233], v[178:181]
	v_mfma_f32_16x16x32_bf16 v[34:37], v[198:201], v[234:237], v[182:185]
	v_mfma_f32_16x16x32_bf16 v[6:9], v[194:197], v[238:241], v[6:9]
	v_mfma_f32_16x16x32_bf16 v[2:5], v[198:201], v[238:241], v[186:189]
	v_lshl_add_u64 v[178:179], v[134:135], 2, s[22:23]
	v_add_co_u32_e32 v180, vcc, 0x10000, v178
	s_nop 1
	v_bfe_u32 v252, v1, 4, 1
	v_mul_u32_u24_e32 v252, 24, v252
	v_mov_b32_e32 v253, 0
	v_addc_co_u32_e32 v181, vcc, 0, v179, vcc
	v_add_co_u32_e32 v182, vcc, 0x20000, v178
	s_nop 1
	v_addc_co_u32_e32 v183, vcc, 0, v179, vcc
	v_add_co_u32_e32 v184, vcc, 0x30000, v178
	s_nop 1
	v_addc_co_u32_e32 v185, vcc, 0, v179, vcc
	global_load_dword v130, v[178:179], off
	global_load_dword v137, v[180:181], off
	global_load_dword v177, v[182:183], off
	s_nop 0
	global_load_dword v204, v[178:179], off offset:64
	global_load_dword v205, v[180:181], off offset:64
	global_load_dword v206, v[182:183], off offset:64
	global_load_dword v207, v[184:185], off offset:64
	global_load_dword v208, v[178:179], off offset:128
	global_load_dword v209, v[180:181], off offset:128
	global_load_dword v210, v[182:183], off offset:128
	global_load_dword v211, v[184:185], off offset:128
	global_load_dword v212, v[178:179], off offset:192
	global_load_dword v213, v[180:181], off offset:192
	global_load_dword v214, v[182:183], off offset:192
	global_load_dword v215, v[184:185], off offset:192
	global_load_dword v180, v[184:185], off
	v_mov_b64_e32 v[178:179], s[20:21]
	v_mad_u64_u32 v[178:179], s[8:9], v134, s56, v[178:179]
	v_mad_i32_i24 v179, v135, s56, v179
	s_waitcnt vmcnt(0)
	v_add_f32_e32 v130, 0, v130
	v_add_f32_e32 v130, v130, v137
	v_add_f32_e32 v130, v130, v177
	v_add_f32_e32 v130, v130, v180
	v_fmamk_f32 v130, v130, 0x3b000000, v176
	v_mul_f32_e32 v137, 0x4b800000, v130
	v_cmp_gt_f32_e32 vcc, s51, v130
	s_nop 1
	v_cndmask_b32_e32 v130, v130, v137, vcc
	v_rsq_f32_e32 v130, v130
	s_nop 0
	v_mul_f32_e32 v137, 0x45800000, v130
	v_cndmask_b32_e32 v130, v130, v137, vcc
	v_mov_b32_e32 v251, v130
	v_mul_f32_e32 v126, v126, v130
	v_mul_f32_e32 v127, v127, v130
	v_mul_f32_e32 v128, v128, v130
	v_mul_f32_e32 v129, v129, v130
	v_cvt_pk_bf16_f32 v126, v126, v127
	v_cvt_pk_bf16_f32 v127, v128, v129
	v_or_b32_e32 v254, 16, v132
	v_mov_b64_e32 v[254:255], s[20:21]
	v_mad_u64_u32 v[254:255], s[10:11], v134, s56, v[254:255]
	v_mad_i32_i24 v255, v135, s56, v255
	v_mul_f32_e32 v122, v122, v251
	v_mul_f32_e32 v123, v123, v251
	v_mul_f32_e32 v124, v124, v251
	v_mul_f32_e32 v125, v125, v251
	v_cvt_pk_bf16_f32 v128, v122, v123
	v_cvt_pk_bf16_f32 v129, v124, v125
	v_lshl_add_u64 v[124:125], v[132:133], 1, v[254:255]
	s_nop 1
	v_permlane16_swap_b32 v126, v128
	v_permlane16_swap_b32 v127, v129
	v_lshl_add_u64 v[254:255], v[124:125], 0, v[252:253]
	s_nop 0
	global_store_dwordx4 v[254:255], v[126:129], off
	s_nop 1
	v_or_b32_e32 v122, 32, v132
	v_mov_b64_e32 v[122:123], s[20:21]
	v_mad_u64_u32 v[122:123], s[12:13], v134, s56, v[122:123]
	v_mad_i32_i24 v123, v135, s56, v123
	v_mul_f32_e32 v118, v118, v251
	v_mul_f32_e32 v119, v119, v251
	v_mul_f32_e32 v120, v120, v251
	v_mul_f32_e32 v121, v121, v251
	v_cvt_pk_bf16_f32 v118, v118, v119
	v_cvt_pk_bf16_f32 v119, v120, v121
	v_or_b32_e32 v254, 48, v132
	v_mov_b64_e32 v[254:255], s[20:21]
	v_mad_u64_u32 v[254:255], s[14:15], v134, s56, v[254:255]
	v_mad_i32_i24 v255, v135, s56, v255
	v_mul_f32_e32 v114, v114, v251
	v_mul_f32_e32 v115, v115, v251
	v_mul_f32_e32 v116, v116, v251
	v_mul_f32_e32 v117, v117, v251
	v_cvt_pk_bf16_f32 v120, v114, v115
	v_cvt_pk_bf16_f32 v121, v116, v117
	v_lshl_add_u64 v[116:117], v[132:133], 1, v[254:255]
	s_nop 1
	v_permlane16_swap_b32 v118, v120
	v_permlane16_swap_b32 v119, v121
	v_lshl_add_u64 v[254:255], v[116:117], 0, v[252:253]
	s_nop 0
	global_store_dwordx4 v[254:255], v[118:121], off offset:64
	s_nop 1
	v_or_b32_e32 v114, 64, v132
	v_mov_b64_e32 v[114:115], s[20:21]
	v_mad_u64_u32 v[114:115], s[16:17], v134, s56, v[114:115]
	v_mad_i32_i24 v115, v135, s56, v115
	v_mul_f32_e32 v110, v110, v251
	v_mul_f32_e32 v111, v111, v251
	v_mul_f32_e32 v112, v112, v251
	v_mul_f32_e32 v113, v113, v251
	v_cvt_pk_bf16_f32 v110, v110, v111
	v_cvt_pk_bf16_f32 v111, v112, v113
	v_or_b32_e32 v254, 0x50, v132
	v_mov_b64_e32 v[254:255], s[20:21]
	v_mad_u64_u32 v[254:255], s[18:19], v134, s56, v[254:255]
	v_mad_i32_i24 v255, v135, s56, v255
	v_mul_f32_e32 v106, v106, v251
	v_mul_f32_e32 v107, v107, v251
	v_mul_f32_e32 v108, v108, v251
	v_mul_f32_e32 v109, v109, v251
	v_cvt_pk_bf16_f32 v112, v106, v107
	v_cvt_pk_bf16_f32 v113, v108, v109
; __device__ __forceinline__ int get_tid512() { int t = threadIdx.x; asm volatile("" : "+v"(t)); return t; }
; __device__ __forceinline__ unsigned pack2(float a, float b) { unsigned r; asm("v_cvt_pk_bf16_f32 %0, %1, %2" : "=v"(r) : "v"(a), "v"(b)); return r; }
;   __device__ __forceinline__ void c4(int g, int rig, int col, f32x4 v) const {
;     const size_t row = (size_t)g * ostride + rig;
;     float s = 1.f;
;     if (NP > 0) {
;       float t = 0.f;
; #pragma unroll
;       for (int q = 0; q < NP; ++q) t += part[(size_t)q * pstride + row];
;       s = rsqrtf(t * inv_n + 1e-6f);
;     }
;     uint2 u; u.x = pack2(v[0] * s, v[1] * s); u.y = pack2(v[2] * s, v[3] * s);
;     *(uint2*)(out + row * ld + col) = u;
;   }
; template <bool SWAP, class Epi, bool THIN = false> ...
;     ...
;     const int te = get_tid512();
;     const int fr_e = te & 15, fq_e = (te & 63) >> 4, wr_e = te >> 7, wc_e = (te >> 6) & 1;
;     const int sub = 2 * mt + (wr_e >> 1);
;     const int g = sub / tpg, ti = sub - g * tpg;
;     const int rig0 = ti * step - halo;
;     const int rw = (wr_e & 1) * 64;
;     if constexpr (Epi::KIND == 0) {
; #pragma unroll
;       for (int m = 0; m < 4; ++m) {
;         const int rig = rig0 + rw + m * 16 + fr_e;
;         if constexpr (Epi::ROWSUM) {
;           float ss = 0.f;
; #pragma unroll
;           for (int n = 0; n < 8; ++n) {
;             const int col = nt * 256 + wc_e * 128 + n * 16 + fq_e * 4;
;             if (col < N) ss += epi.c4(g, rig, col, acc[m][n]);
;           }
;           ss += __shfl_xor(ss, 16); ss += __shfl_xor(ss, 32);
;           if (fq_e == 0) epi.rowsum(g, rig, nt * 2 + wc_e, ss);
;         } else {
; #pragma unroll
;           for (int n = 0; n < 8; ++n) {
;             const int col = nt * 256 + wc_e * 128 + n * 16 + fq_e * 4;
;             if (col < N) epi.c4(g, rig, col, acc[m][n]);
;           }
	v_lshl_add_u64 v[108:109], v[132:133], 1, v[254:255]
	s_nop 1
	v_permlane16_swap_b32 v110, v112
	v_permlane16_swap_b32 v111, v113
	v_lshl_add_u64 v[254:255], v[108:109], 0, v[252:253]
	s_nop 0
	global_store_dwordx4 v[254:255], v[110:113], off offset:128
	s_nop 1
	v_or_b32_e32 v106, 0x60, v132
	v_mov_b64_e32 v[106:107], s[20:21]
	v_mad_u64_u32 v[106:107], s[44:45], v134, s56, v[106:107]
	v_mad_i32_i24 v107, v135, s56, v107
	v_mul_f32_e32 v102, v102, v251
	v_mul_f32_e32 v103, v103, v251
	v_mul_f32_e32 v104, v104, v251
	v_mul_f32_e32 v105, v105, v251
	v_cvt_pk_bf16_f32 v102, v102, v103
	v_cvt_pk_bf16_f32 v103, v104, v105
	v_or_b32_e32 v254, 0x70, v132
	v_mov_b64_e32 v[254:255], s[20:21]
	v_mad_u64_u32 v[254:255], s[58:59], v134, s56, v[254:255]
	v_mad_i32_i24 v255, v135, s56, v255
	v_mul_f32_e32 v98, v98, v251
	v_mul_f32_e32 v99, v99, v251
	v_mul_f32_e32 v100, v100, v251
	v_mul_f32_e32 v101, v101, v251
	v_cvt_pk_bf16_f32 v104, v98, v99
	v_cvt_pk_bf16_f32 v105, v100, v101
	v_lshl_add_u64 v[100:101], v[132:133], 1, v[254:255]
	s_nop 1
	v_permlane16_swap_b32 v102, v104
	v_permlane16_swap_b32 v103, v105
	v_lshl_add_u64 v[254:255], v[100:101], 0, v[252:253]
	s_nop 0
	global_store_dwordx4 v[254:255], v[102:105], off offset:192
	s_nop 1
	v_or_b32_e32 v98, 16, v136
	v_ashrrev_i32_e32 v99, 31, v98
	v_lshl_add_u64 v[98:99], v[138:139], 0, v[98:99]
	v_lshl_add_u64 v[100:101], v[134:135], 2, s[22:23]
	v_add_co_u32_e32 v102, vcc, 0x10000, v100
	s_nop 1
	v_addc_co_u32_e32 v103, vcc, 0, v101, vcc
	v_add_co_u32_e32 v104, vcc, 0x20000, v100
	s_nop 1
	v_addc_co_u32_e32 v105, vcc, 0, v101, vcc
	v_add_co_u32_e32 v106, vcc, 0x30000, v100
	s_nop 1
	v_addc_co_u32_e32 v107, vcc, 0, v101, vcc
	s_nop 0
	s_nop 0
	s_nop 0
	v_mov_b64_e32 v[100:101], s[20:21]
	v_mad_u64_u32 v[100:101], s[58:59], v98, s56, v[100:101]
	v_mad_i32_i24 v101, v99, s56, v101
	v_add_f32_e32 v105, 0, v204
	v_add_f32_e32 v102, v105, v205
	v_add_f32_e32 v102, v102, v206
	v_add_f32_e32 v102, v102, v207
	v_fmamk_f32 v102, v102, 0x3b000000, v176
	v_mul_f32_e32 v103, 0x4b800000, v102
	v_cmp_gt_f32_e32 vcc, s51, v102
	s_nop 1
	v_cndmask_b32_e32 v102, v102, v103, vcc
	v_rsq_f32_e32 v102, v102
	s_nop 0
	v_mul_f32_e32 v103, 0x45800000, v102
	v_cndmask_b32_e32 v102, v102, v103, vcc
	v_mov_b32_e32 v251, v102
	v_mul_f32_e32 v94, v94, v102
	v_mul_f32_e32 v95, v95, v102
	v_mul_f32_e32 v96, v96, v102
	v_mul_f32_e32 v97, v97, v102
	v_cvt_pk_bf16_f32 v94, v94, v95
	v_cvt_pk_bf16_f32 v95, v96, v97
	v_mov_b64_e32 v[254:255], s[20:21]
	v_mad_u64_u32 v[254:255], s[58:59], v98, s56, v[254:255]
	v_mad_i32_i24 v255, v99, s56, v255
	v_mul_f32_e32 v90, v90, v251
	v_mul_f32_e32 v91, v91, v251
	v_mul_f32_e32 v92, v92, v251
	v_mul_f32_e32 v93, v93, v251
	v_cvt_pk_bf16_f32 v96, v90, v91
	v_cvt_pk_bf16_f32 v97, v92, v93
	v_lshl_add_u64 v[92:93], v[132:133], 1, v[254:255]
	s_nop 1
	v_permlane16_swap_b32 v94, v96
	v_permlane16_swap_b32 v95, v97
	v_lshl_add_u64 v[254:255], v[92:93], 0, v[252:253]
	s_nop 0
	global_store_dwordx4 v[254:255], v[94:97], off
	s_nop 1
	v_mov_b64_e32 v[90:91], s[20:21]
	v_mad_u64_u32 v[90:91], s[58:59], v98, s56, v[90:91]
	v_mad_i32_i24 v91, v99, s56, v91
	v_mul_f32_e32 v86, v86, v251
	v_mul_f32_e32 v87, v87, v251
	v_mul_f32_e32 v88, v88, v251
	v_mul_f32_e32 v89, v89, v251
	v_cvt_pk_bf16_f32 v86, v86, v87
	v_cvt_pk_bf16_f32 v87, v88, v89
	v_mov_b64_e32 v[254:255], s[20:21]
	v_mad_u64_u32 v[254:255], s[58:59], v98, s56, v[254:255]
	v_mad_i32_i24 v255, v99, s56, v255
	v_mul_f32_e32 v82, v82, v251
	v_mul_f32_e32 v83, v83, v251
	v_mul_f32_e32 v84, v84, v251
	v_mul_f32_e32 v85, v85, v251
	v_cvt_pk_bf16_f32 v88, v82, v83
	v_cvt_pk_bf16_f32 v89, v84, v85
	v_lshl_add_u64 v[84:85], v[132:133], 1, v[254:255]
	s_nop 1
	v_permlane16_swap_b32 v86, v88
	v_permlane16_swap_b32 v87, v89
	v_lshl_add_u64 v[254:255], v[84:85], 0, v[252:253]
	s_nop 0
	global_store_dwordx4 v[254:255], v[86:89], off offset:64
	s_nop 1
	v_mov_b64_e32 v[82:83], s[20:21]
	v_mad_u64_u32 v[82:83], s[58:59], v98, s56, v[82:83]
	v_mad_i32_i24 v83, v99, s56, v83
	v_mul_f32_e32 v78, v78, v251
	v_mul_f32_e32 v79, v79, v251
	v_mul_f32_e32 v80, v80, v251
	v_mul_f32_e32 v81, v81, v251
	v_cvt_pk_bf16_f32 v78, v78, v79
	v_cvt_pk_bf16_f32 v79, v80, v81
	v_mov_b64_e32 v[254:255], s[20:21]
	v_mad_u64_u32 v[254:255], s[58:59], v98, s56, v[254:255]
	v_mad_i32_i24 v255, v99, s56, v255
	v_mul_f32_e32 v74, v74, v251
	v_mul_f32_e32 v75, v75, v251
	v_mul_f32_e32 v76, v76, v251
	v_mul_f32_e32 v77, v77, v251
	v_cvt_pk_bf16_f32 v80, v74, v75
	v_cvt_pk_bf16_f32 v81, v76, v77
	v_lshl_add_u64 v[76:77], v[132:133], 1, v[254:255]
	s_nop 1
	v_permlane16_swap_b32 v78, v80
	v_permlane16_swap_b32 v79, v81
	v_lshl_add_u64 v[254:255], v[76:77], 0, v[252:253]
	s_nop 0
	global_store_dwordx4 v[254:255], v[78:81], off offset:128
	s_nop 1
	v_mov_b64_e32 v[74:75], s[20:21]
	v_mad_u64_u32 v[74:75], s[58:59], v98, s56, v[74:75]
	v_mad_i32_i24 v75, v99, s56, v75
	v_mul_f32_e32 v70, v70, v251
	v_mul_f32_e32 v71, v71, v251
	v_mul_f32_e32 v72, v72, v251
	v_mul_f32_e32 v73, v73, v251
	v_cvt_pk_bf16_f32 v70, v70, v71
	v_cvt_pk_bf16_f32 v71, v72, v73
	v_mov_b64_e32 v[254:255], s[20:21]
	v_mad_u64_u32 v[254:255], s[58:59], v98, s56, v[254:255]
	v_mad_i32_i24 v255, v99, s56, v255
	v_mul_f32_e32 v66, v66, v251
	v_mul_f32_e32 v67, v67, v251
	v_mul_f32_e32 v68, v68, v251
	v_mul_f32_e32 v69, v69, v251
	v_cvt_pk_bf16_f32 v72, v66, v67
	v_cvt_pk_bf16_f32 v73, v68, v69
	v_lshl_add_u64 v[68:69], v[132:133], 1, v[254:255]
	s_nop 1
	v_permlane16_swap_b32 v70, v72
	v_permlane16_swap_b32 v71, v73
	v_lshl_add_u64 v[254:255], v[68:69], 0, v[252:253]
	s_nop 0
	global_store_dwordx4 v[254:255], v[70:73], off offset:192
; __device__ __forceinline__ int get_tid512() { int t = threadIdx.x; asm volatile("" : "+v"(t)); return t; }
; __device__ __forceinline__ unsigned pack2(float a, float b) { unsigned r; asm("v_cvt_pk_bf16_f32 %0, %1, %2" : "=v"(r) : "v"(a), "v"(b)); return r; }
;   __device__ __forceinline__ void c4(int g, int rig, int col, f32x4 v) const {
;     const size_t row = (size_t)g * ostride + rig;
;     float s = 1.f;
;     if (NP > 0) {
;       float t = 0.f;
; #pragma unroll
;       for (int q = 0; q < NP; ++q) t += part[(size_t)q * pstride + row];
;       s = rsqrtf(t * inv_n + 1e-6f);
;     }
;     uint2 u; u.x = pack2(v[0] * s, v[1] * s); u.y = pack2(v[2] * s, v[3] * s);
;     *(uint2*)(out + row * ld + col) = u;
;   }
; template <bool SWAP, class Epi, bool THIN = false> ...
;     ...
;     const int te = get_tid512();
;     const int fr_e = te & 15, fq_e = (te & 63) >> 4, wr_e = te >> 7, wc_e = (te >> 6) & 1;
;     const int sub = 2 * mt + (wr_e >> 1);
;     const int g = sub / tpg, ti = sub - g * tpg;
;     const int rig0 = ti * step - halo;
;     const int rw = (wr_e & 1) * 64;
;     if constexpr (Epi::KIND == 0) {
; #pragma unroll
;       for (int m = 0; m < 4; ++m) {
;         const int rig = rig0 + rw + m * 16 + fr_e;
;         if constexpr (Epi::ROWSUM) {
;           float ss = 0.f;
; #pragma unroll
;           for (int n = 0; n < 8; ++n) {
;             const int col = nt * 256 + wc_e * 128 + n * 16 + fq_e * 4;
;             if (col < N) ss += epi.c4(g, rig, col, acc[m][n]);
;           }
;           ss += __shfl_xor(ss, 16); ss += __shfl_xor(ss, 32);
;           if (fq_e == 0) epi.rowsum(g, rig, nt * 2 + wc_e, ss);
;         } else {
; #pragma unroll
;           for (int n = 0; n < 8; ++n) {
;             const int col = nt * 256 + wc_e * 128 + n * 16 + fq_e * 4;
;             if (col < N) epi.c4(g, rig, col, acc[m][n]);
;           }
	s_nop 1
	v_or_b32_e32 v66, 32, v136
	v_ashrrev_i32_e32 v67, 31, v66
	v_lshl_add_u64 v[66:67], v[138:139], 0, v[66:67]
	v_lshl_add_u64 v[68:69], v[134:135], 2, s[22:23]
	v_add_co_u32_e32 v70, vcc, 0x10000, v68
	s_nop 1
	v_addc_co_u32_e32 v71, vcc, 0, v69, vcc
	v_add_co_u32_e32 v72, vcc, 0x20000, v68
	s_nop 1
	v_addc_co_u32_e32 v73, vcc, 0, v69, vcc
	v_add_co_u32_e32 v74, vcc, 0x30000, v68
	s_nop 1
	v_addc_co_u32_e32 v75, vcc, 0, v69, vcc
	s_nop 0
	s_nop 0
	s_nop 0
	v_mov_b64_e32 v[68:69], s[20:21]
	v_mad_u64_u32 v[68:69], s[58:59], v66, s56, v[68:69]
	v_mad_i32_i24 v69, v67, s56, v69
	v_add_f32_e32 v73, 0, v208
	v_add_f32_e32 v70, v73, v209
	v_add_f32_e32 v70, v70, v210
	v_add_f32_e32 v70, v70, v211
	v_fmamk_f32 v70, v70, 0x3b000000, v176
	v_mul_f32_e32 v71, 0x4b800000, v70
	v_cmp_gt_f32_e32 vcc, s51, v70
	s_nop 1
	v_cndmask_b32_e32 v70, v70, v71, vcc
	v_rsq_f32_e32 v70, v70
	s_nop 0
	v_mul_f32_e32 v71, 0x45800000, v70
	v_cndmask_b32_e32 v70, v70, v71, vcc
	v_mov_b32_e32 v251, v70
	v_mul_f32_e32 v62, v62, v70
	v_mul_f32_e32 v63, v63, v70
	v_mul_f32_e32 v64, v64, v70
	v_mul_f32_e32 v65, v65, v70
	v_cvt_pk_bf16_f32 v62, v62, v63
	v_cvt_pk_bf16_f32 v63, v64, v65
	v_mov_b64_e32 v[254:255], s[20:21]
	v_mad_u64_u32 v[254:255], s[58:59], v66, s56, v[254:255]
	v_mad_i32_i24 v255, v67, s56, v255
	v_mul_f32_e32 v58, v58, v251
	v_mul_f32_e32 v59, v59, v251
	v_mul_f32_e32 v60, v60, v251
	v_mul_f32_e32 v61, v61, v251
	v_cvt_pk_bf16_f32 v64, v58, v59
	v_cvt_pk_bf16_f32 v65, v60, v61
	v_lshl_add_u64 v[60:61], v[132:133], 1, v[254:255]
	s_nop 1
	v_permlane16_swap_b32 v62, v64
	v_permlane16_swap_b32 v63, v65
	v_lshl_add_u64 v[254:255], v[60:61], 0, v[252:253]
	s_nop 0
	global_store_dwordx4 v[254:255], v[62:65], off
	s_nop 1
	v_mov_b64_e32 v[58:59], s[20:21]
	v_mad_u64_u32 v[58:59], s[58:59], v66, s56, v[58:59]
	v_mad_i32_i24 v59, v67, s56, v59
	v_mul_f32_e32 v54, v54, v251
	v_mul_f32_e32 v55, v55, v251
	v_mul_f32_e32 v56, v56, v251
	v_mul_f32_e32 v57, v57, v251
	v_cvt_pk_bf16_f32 v54, v54, v55
	v_cvt_pk_bf16_f32 v55, v56, v57
	v_mov_b64_e32 v[254:255], s[20:21]
	v_mad_u64_u32 v[254:255], s[58:59], v66, s56, v[254:255]
	v_mad_i32_i24 v255, v67, s56, v255
	v_mul_f32_e32 v50, v50, v251
	v_mul_f32_e32 v51, v51, v251
	v_mul_f32_e32 v52, v52, v251
	v_mul_f32_e32 v53, v53, v251
	v_cvt_pk_bf16_f32 v56, v50, v51
	v_cvt_pk_bf16_f32 v57, v52, v53
	v_lshl_add_u64 v[52:53], v[132:133], 1, v[254:255]
	s_nop 1
	v_permlane16_swap_b32 v54, v56
	v_permlane16_swap_b32 v55, v57
	v_lshl_add_u64 v[254:255], v[52:53], 0, v[252:253]
	s_nop 0
	global_store_dwordx4 v[254:255], v[54:57], off offset:64
	s_nop 1
	v_mov_b64_e32 v[50:51], s[20:21]
	v_mad_u64_u32 v[50:51], s[58:59], v66, s56, v[50:51]
	v_mad_i32_i24 v51, v67, s56, v51
	v_mul_f32_e32 v46, v46, v251
	v_mul_f32_e32 v47, v47, v251
	v_mul_f32_e32 v48, v48, v251
	v_mul_f32_e32 v49, v49, v251
	v_cvt_pk_bf16_f32 v46, v46, v47
	v_cvt_pk_bf16_f32 v47, v48, v49
	v_mov_b64_e32 v[254:255], s[20:21]
	v_mad_u64_u32 v[254:255], s[58:59], v66, s56, v[254:255]
	v_mad_i32_i24 v255, v67, s56, v255
	v_mul_f32_e32 v42, v42, v251
	v_mul_f32_e32 v43, v43, v251
	v_mul_f32_e32 v44, v44, v251
	v_mul_f32_e32 v45, v45, v251
	v_cvt_pk_bf16_f32 v48, v42, v43
	v_cvt_pk_bf16_f32 v49, v44, v45
	v_lshl_add_u64 v[44:45], v[132:133], 1, v[254:255]
	s_nop 1
	v_permlane16_swap_b32 v46, v48
	v_permlane16_swap_b32 v47, v49
	v_lshl_add_u64 v[254:255], v[44:45], 0, v[252:253]
	s_nop 0
	global_store_dwordx4 v[254:255], v[46:49], off offset:128
	s_nop 1
	v_mov_b64_e32 v[42:43], s[20:21]
	v_mad_u64_u32 v[42:43], s[58:59], v66, s56, v[42:43]
	v_mad_i32_i24 v43, v67, s56, v43
	v_mul_f32_e32 v38, v38, v251
	v_mul_f32_e32 v39, v39, v251
	v_mul_f32_e32 v40, v40, v251
	v_mul_f32_e32 v41, v41, v251
	v_cvt_pk_bf16_f32 v38, v38, v39
	v_cvt_pk_bf16_f32 v39, v40, v41
	v_mov_b64_e32 v[254:255], s[20:21]
	v_mad_u64_u32 v[254:255], s[58:59], v66, s56, v[254:255]
	v_mad_i32_i24 v255, v67, s56, v255
	v_mul_f32_e32 v34, v34, v251
	v_mul_f32_e32 v35, v35, v251
	v_mul_f32_e32 v36, v36, v251
	v_mul_f32_e32 v37, v37, v251
	v_cvt_pk_bf16_f32 v40, v34, v35
	v_cvt_pk_bf16_f32 v41, v36, v37
	v_lshl_add_u64 v[36:37], v[132:133], 1, v[254:255]
	s_nop 1
	v_permlane16_swap_b32 v38, v40
	v_permlane16_swap_b32 v39, v41
	v_lshl_add_u64 v[254:255], v[36:37], 0, v[252:253]
	s_nop 0
	global_store_dwordx4 v[254:255], v[38:41], off offset:192
; __device__ __forceinline__ int get_tid512() { int t = threadIdx.x; asm volatile("" : "+v"(t)); return t; }
; __device__ __forceinline__ unsigned pack2(float a, float b) { unsigned r; asm("v_cvt_pk_bf16_f32 %0, %1, %2" : "=v"(r) : "v"(a), "v"(b)); return r; }
;   __device__ __forceinline__ void c4(int g, int rig, int col, f32x4 v) const {
;     const size_t row = (size_t)g * ostride + rig;
;     float s = 1.f;
;     if (NP > 0) {
;       float t = 0.f;
; #pragma unroll
;       for (int q = 0; q < NP; ++q) t += part[(size_t)q * pstride + row];
;       s = rsqrtf(t * inv_n + 1e-6f);
;     }
;     uint2 u; u.x = pack2(v[0] * s, v[1] * s); u.y = pack2(v[2] * s, v[3] * s);
;     *(uint2*)(out + row * ld + col) = u;
;   }
; template <bool SWAP, class Epi, bool THIN = false> ...
;     ...
;     const int te = get_tid512();
;     const int fr_e = te & 15, fq_e = (te & 63) >> 4, wr_e = te >> 7, wc_e = (te >> 6) & 1;
;     const int sub = 2 * mt + (wr_e >> 1);
;     const int g = sub / tpg, ti = sub - g * tpg;
;     const int rig0 = ti * step - halo;
;     const int rw = (wr_e & 1) * 64;
;     if constexpr (Epi::KIND == 0) {
; #pragma unroll
;       for (int m = 0; m < 4; ++m) {
;         const int rig = rig0 + rw + m * 16 + fr_e;
;         if constexpr (Epi::ROWSUM) {
;           float ss = 0.f;
; #pragma unroll
;           for (int n = 0; n < 8; ++n) {
;             const int col = nt * 256 + wc_e * 128 + n * 16 + fq_e * 4;
;             if (col < N) ss += epi.c4(g, rig, col, acc[m][n]);
;           }
;           ss += __shfl_xor(ss, 16); ss += __shfl_xor(ss, 32);
;           if (fq_e == 0) epi.rowsum(g, rig, nt * 2 + wc_e, ss);
;         } else {
; #pragma unroll
;           for (int n = 0; n < 8; ++n) {
;             const int col = nt * 256 + wc_e * 128 + n * 16 + fq_e * 4;
;             if (col < N) epi.c4(g, rig, col, acc[m][n]);
;           }
	s_nop 1
	v_or_b32_e32 v34, 48, v136
	v_ashrrev_i32_e32 v35, 31, v34
	v_lshl_add_u64 v[34:35], v[138:139], 0, v[34:35]
	v_lshl_add_u64 v[36:37], v[134:135], 2, s[22:23]
	v_add_co_u32_e32 v38, vcc, 0x10000, v36
	s_nop 1
	v_addc_co_u32_e32 v39, vcc, 0, v37, vcc
	v_add_co_u32_e32 v40, vcc, 0x20000, v36
	s_nop 1
	v_addc_co_u32_e32 v41, vcc, 0, v37, vcc
	v_add_co_u32_e32 v42, vcc, 0x30000, v36
	s_nop 1
	v_addc_co_u32_e32 v43, vcc, 0, v37, vcc
	s_nop 0
	s_nop 0
	s_nop 0
	v_mov_b64_e32 v[36:37], s[20:21]
	v_mad_u64_u32 v[36:37], s[4:5], v34, s56, v[36:37]
	v_mad_i32_i24 v37, v35, s56, v37
	v_add_f32_e32 v41, 0, v212
	v_add_f32_e32 v38, v41, v213
	v_add_f32_e32 v38, v38, v214
	v_add_f32_e32 v38, v38, v215
	v_fmamk_f32 v38, v38, 0x3b000000, v176
	v_mul_f32_e32 v39, 0x4b800000, v38
	v_cmp_gt_f32_e32 vcc, s51, v38
	s_nop 1
	v_cndmask_b32_e32 v38, v38, v39, vcc
	v_rsq_f32_e32 v38, v38
	s_nop 0
	v_mul_f32_e32 v39, 0x45800000, v38
	v_cndmask_b32_e32 v38, v38, v39, vcc
	v_mov_b32_e32 v251, v38
	v_mul_f32_e32 v30, v30, v38
	v_mul_f32_e32 v31, v31, v38
	v_mul_f32_e32 v32, v32, v38
	v_mul_f32_e32 v33, v33, v38
	v_cvt_pk_bf16_f32 v30, v30, v31
	v_cvt_pk_bf16_f32 v31, v32, v33
	v_mov_b64_e32 v[254:255], s[20:21]
	v_mad_u64_u32 v[254:255], s[6:7], v34, s56, v[254:255]
	v_mad_i32_i24 v255, v35, s56, v255
	v_mul_f32_e32 v26, v26, v251
	v_mul_f32_e32 v27, v27, v251
	v_mul_f32_e32 v28, v28, v251
	v_mul_f32_e32 v29, v29, v251
	v_cvt_pk_bf16_f32 v32, v26, v27
	v_cvt_pk_bf16_f32 v33, v28, v29
	v_lshl_add_u64 v[28:29], v[132:133], 1, v[254:255]
	s_nop 1
	v_permlane16_swap_b32 v30, v32
	v_permlane16_swap_b32 v31, v33
	v_lshl_add_u64 v[254:255], v[28:29], 0, v[252:253]
	s_nop 0
	global_store_dwordx4 v[254:255], v[30:33], off
	s_nop 1
	v_mov_b64_e32 v[26:27], s[20:21]
	v_mad_u64_u32 v[26:27], s[6:7], v34, s56, v[26:27]
	v_mad_i32_i24 v27, v35, s56, v27
	v_mul_f32_e32 v22, v22, v251
	v_mul_f32_e32 v23, v23, v251
	v_mul_f32_e32 v24, v24, v251
	v_mul_f32_e32 v25, v25, v251
	v_cvt_pk_bf16_f32 v22, v22, v23
	v_cvt_pk_bf16_f32 v23, v24, v25
	v_mov_b64_e32 v[254:255], s[20:21]
	v_mad_u64_u32 v[254:255], s[6:7], v34, s56, v[254:255]
	v_mad_i32_i24 v255, v35, s56, v255
	v_mul_f32_e32 v18, v18, v251
	v_mul_f32_e32 v19, v19, v251
	v_mul_f32_e32 v20, v20, v251
	v_mul_f32_e32 v21, v21, v251
	v_cvt_pk_bf16_f32 v24, v18, v19
	v_cvt_pk_bf16_f32 v25, v20, v21
	v_lshl_add_u64 v[20:21], v[132:133], 1, v[254:255]
	s_nop 1
	v_permlane16_swap_b32 v22, v24
	v_permlane16_swap_b32 v23, v25
	v_lshl_add_u64 v[254:255], v[20:21], 0, v[252:253]
	s_nop 0
	global_store_dwordx4 v[254:255], v[22:25], off offset:64
	s_nop 1
	v_mov_b64_e32 v[18:19], s[20:21]
	v_mad_u64_u32 v[18:19], s[6:7], v34, s56, v[18:19]
	v_mad_i32_i24 v19, v35, s56, v19
	v_mul_f32_e32 v14, v14, v251
	v_mul_f32_e32 v15, v15, v251
	v_mul_f32_e32 v16, v16, v251
	v_mul_f32_e32 v17, v17, v251
	v_cvt_pk_bf16_f32 v14, v14, v15
	v_cvt_pk_bf16_f32 v15, v16, v17
	v_mov_b64_e32 v[254:255], s[20:21]
	v_mad_u64_u32 v[254:255], s[6:7], v34, s56, v[254:255]
	v_mad_i32_i24 v255, v35, s56, v255
	v_mul_f32_e32 v10, v10, v251
	v_mul_f32_e32 v11, v11, v251
	v_mul_f32_e32 v12, v12, v251
	v_mul_f32_e32 v13, v13, v251
	v_cvt_pk_bf16_f32 v16, v10, v11
	v_cvt_pk_bf16_f32 v17, v12, v13
	v_lshl_add_u64 v[12:13], v[132:133], 1, v[254:255]
	s_nop 1
	v_permlane16_swap_b32 v14, v16
	v_permlane16_swap_b32 v15, v17
	v_lshl_add_u64 v[254:255], v[12:13], 0, v[252:253]
	s_nop 0
	global_store_dwordx4 v[254:255], v[14:17], off offset:128
	s_nop 1
	v_mov_b64_e32 v[10:11], s[20:21]
	v_mad_u64_u32 v[10:11], s[6:7], v34, s56, v[10:11]
	v_mad_i32_i24 v11, v35, s56, v11
	v_mul_f32_e32 v6, v6, v251
	v_mul_f32_e32 v7, v7, v251
	v_mul_f32_e32 v8, v8, v251
	v_mul_f32_e32 v9, v9, v251
	v_cvt_pk_bf16_f32 v6, v6, v7
	v_cvt_pk_bf16_f32 v7, v8, v9
	v_mov_b64_e32 v[254:255], s[20:21]
	v_mad_u64_u32 v[254:255], s[6:7], v34, s56, v[254:255]
	v_mad_i32_i24 v255, v35, s56, v255
	v_mul_f32_e32 v2, v2, v251
	v_mul_f32_e32 v3, v3, v251
	v_mul_f32_e32 v4, v4, v251
	v_mul_f32_e32 v5, v5, v251
	v_cvt_pk_bf16_f32 v8, v2, v3
	v_cvt_pk_bf16_f32 v9, v4, v5
	v_lshl_add_u64 v[4:5], v[132:133], 1, v[254:255]
	s_nop 1
	v_permlane16_swap_b32 v6, v8
	v_permlane16_swap_b32 v7, v9
	v_lshl_add_u64 v[254:255], v[4:5], 0, v[252:253]
	s_nop 0
	global_store_dwordx4 v[254:255], v[6:9], off offset:192
	s_nop 1
	s_branch .LBB0_1748
